# GEMM main loops: scalar bookkeeping that trailed MFMA clusters (m0 setup, pointer and loop-counter updates) moved into the neighbouring load segments so nothing but a wait sits between a barrier and i
# baseline (speedup 1.0000x reference)
.LBB0_227:
	s_add_u32 s22, s20, 0xfff80080
	s_addc_u32 s23, s21, -1
	s_add_i32 s59, 0, 0x10000
	ds_read_b128 v[140:143], v234
	ds_read_b128 v[144:147], v234 offset:1024
	ds_read_b128 v[148:151], v234 offset:2048
	ds_read_b128 v[170:173], v234 offset:3072
	s_cmp_eq_u32 s58, 28
	s_cselect_b32 s43, s5, s23
	s_cselect_b32 s42, s6, s22
	s_cselect_b32 s23, s7, s57
	s_cselect_b32 s22, s25, s35
	s_add_i32 m0, s49, 0xc000
	ds_read_b128 v[174:177], v168
	ds_read_b128 v[178:181], v168 offset:1024
	ds_read_b128 v[182:185], v168 offset:2048
	ds_read_b128 v[186:189], v168 offset:3072
	ds_read_b128 v[190:193], v168 offset:4096
	ds_read_b128 v[206:209], v168 offset:5120
	ds_read_b128 v[210:213], v168 offset:6144
	ds_read_b128 v[214:217], v168 offset:7168
	global_load_lds_dwordx4 v136, s[20:21]
	s_add_i32 m0, s49, 0xe000
	s_nop 0
	global_load_lds_dwordx4 v138, s[20:21]
	s_waitcnt lgkmcnt(8)
	s_barrier
	s_waitcnt lgkmcnt(0)
	v_mfma_f32_16x16x32_bf16 v[124:127], v[140:143], v[174:177], v[124:127]
	v_mfma_f32_16x16x32_bf16 v[120:123], v[148:151], v[174:177], v[120:123]
	v_mfma_f32_16x16x32_bf16 v[108:111], v[140:143], v[182:185], v[108:111]
	v_mfma_f32_16x16x32_bf16 v[104:107], v[148:151], v[182:185], v[104:107]
	v_mfma_f32_16x16x32_bf16 v[92:95], v[140:143], v[190:193], v[92:95]
	v_mfma_f32_16x16x32_bf16 v[88:91], v[148:151], v[190:193], v[88:91]
	v_mfma_f32_16x16x32_bf16 v[76:79], v[140:143], v[210:213], v[76:79]
	v_mfma_f32_16x16x32_bf16 v[72:75], v[148:151], v[210:213], v[72:75]
	v_mfma_f32_16x16x32_bf16 v[124:127], v[144:147], v[178:181], v[124:127]
	v_mfma_f32_16x16x32_bf16 v[120:123], v[170:173], v[178:181], v[120:123]
	v_mfma_f32_16x16x32_bf16 v[108:111], v[144:147], v[186:189], v[108:111]
	v_mfma_f32_16x16x32_bf16 v[104:107], v[170:173], v[186:189], v[104:107]
	v_mfma_f32_16x16x32_bf16 v[92:95], v[144:147], v[206:209], v[92:95]
	v_mfma_f32_16x16x32_bf16 v[88:91], v[170:173], v[206:209], v[88:91]
	v_mfma_f32_16x16x32_bf16 v[76:79], v[144:147], v[214:217], v[76:79]
	v_mfma_f32_16x16x32_bf16 v[72:75], v[170:173], v[214:217], v[72:75]
	s_barrier
	s_add_i32 s62, 0, 0x14000
	s_add_i32 s59, s59, s48
	s_mov_b32 m0, s59
	ds_read_b128 v[218:221], v235
	ds_read_b128 v[222:225], v235 offset:1024
	ds_read_b128 v[226:229], v235 offset:2048
	ds_read_b128 v[230:233], v235 offset:3072
	global_load_lds_dwordx4 v130, s[22:23]
	s_add_i32 m0, s59, 0x2000
	s_nop 0
	global_load_lds_dwordx4 v134, s[22:23]
	s_barrier
	s_waitcnt lgkmcnt(0)
	v_mfma_f32_16x16x32_bf16 v[116:119], v[218:221], v[174:177], v[116:119]
	v_mfma_f32_16x16x32_bf16 v[112:115], v[226:229], v[174:177], v[112:115]
	v_mfma_f32_16x16x32_bf16 v[100:103], v[218:221], v[182:185], v[100:103]
	v_mfma_f32_16x16x32_bf16 v[96:99], v[226:229], v[182:185], v[96:99]
	v_mfma_f32_16x16x32_bf16 v[84:87], v[218:221], v[190:193], v[84:87]
	v_mfma_f32_16x16x32_bf16 v[80:83], v[226:229], v[190:193], v[80:83]
	v_mfma_f32_16x16x32_bf16 v[68:71], v[218:221], v[210:213], v[68:71]
	v_mfma_f32_16x16x32_bf16 v[64:67], v[226:229], v[210:213], v[64:67]
	v_mfma_f32_16x16x32_bf16 v[116:119], v[222:225], v[178:181], v[116:119]
	v_mfma_f32_16x16x32_bf16 v[112:115], v[230:233], v[178:181], v[112:115]
	v_mfma_f32_16x16x32_bf16 v[100:103], v[222:225], v[186:189], v[100:103]
	v_mfma_f32_16x16x32_bf16 v[96:99], v[230:233], v[186:189], v[96:99]
	v_mfma_f32_16x16x32_bf16 v[84:87], v[222:225], v[206:209], v[84:87]
	v_mfma_f32_16x16x32_bf16 v[80:83], v[230:233], v[206:209], v[80:83]
	v_mfma_f32_16x16x32_bf16 v[68:71], v[222:225], v[214:217], v[68:71]
	v_mfma_f32_16x16x32_bf16 v[64:67], v[230:233], v[214:217], v[64:67]
	s_barrier
	s_mov_b32 m0, s49
	s_add_u32 s98, s42, 0x80
	s_addc_u32 s99, s43, 0
	ds_read_b128 v[174:177], v168 offset:16384
	ds_read_b128 v[178:181], v168 offset:17408
	ds_read_b128 v[182:185], v168 offset:18432
	ds_read_b128 v[186:189], v168 offset:19456
	ds_read_b128 v[190:193], v168 offset:20480
	ds_read_b128 v[206:209], v168 offset:21504
	ds_read_b128 v[210:213], v168 offset:22528
	ds_read_b128 v[214:217], v168 offset:23552
	global_load_lds_dwordx4 v128, s[42:43]
	s_mov_b32 m0, s50
	s_nop 0
	global_load_lds_dwordx4 v132, s[42:43]
	s_barrier
	s_waitcnt lgkmcnt(0)
	v_mfma_f32_16x16x32_bf16 v[60:63], v[140:143], v[174:177], v[60:63]
	v_mfma_f32_16x16x32_bf16 v[56:59], v[148:151], v[174:177], v[56:59]
	v_mfma_f32_16x16x32_bf16 v[48:51], v[140:143], v[182:185], v[48:51]
	v_mfma_f32_16x16x32_bf16 v[40:43], v[148:151], v[182:185], v[40:43]
	v_mfma_f32_16x16x32_bf16 v[32:35], v[140:143], v[190:193], v[32:35]
	v_mfma_f32_16x16x32_bf16 v[24:27], v[148:151], v[190:193], v[24:27]
	v_mfma_f32_16x16x32_bf16 v[16:19], v[140:143], v[210:213], v[16:19]
	v_mfma_f32_16x16x32_bf16 v[8:11], v[148:151], v[210:213], v[8:11]
	v_mfma_f32_16x16x32_bf16 v[60:63], v[144:147], v[178:181], v[60:63]
	v_mfma_f32_16x16x32_bf16 v[56:59], v[170:173], v[178:181], v[56:59]
	v_mfma_f32_16x16x32_bf16 v[48:51], v[144:147], v[186:189], v[48:51]
	v_mfma_f32_16x16x32_bf16 v[40:43], v[170:173], v[186:189], v[40:43]
	v_mfma_f32_16x16x32_bf16 v[32:35], v[144:147], v[206:209], v[32:35]
	v_mfma_f32_16x16x32_bf16 v[24:27], v[170:173], v[206:209], v[24:27]
	v_mfma_f32_16x16x32_bf16 v[16:19], v[144:147], v[214:217], v[16:19]
	v_mfma_f32_16x16x32_bf16 v[8:11], v[170:173], v[214:217], v[8:11]
	s_barrier
	s_add_u32 s60, s22, 0x80000
	s_addc_u32 s61, s23, 0
	s_add_i32 s59, s62, s48
	s_mov_b32 m0, s59
	s_nop 0
	global_load_lds_dwordx4 v130, s[60:61]
	s_add_i32 m0, s59, 0x2000
	s_nop 0
	global_load_lds_dwordx4 v134, s[60:61]
	s_waitcnt vmcnt(6)
	s_barrier
	v_mfma_f32_16x16x32_bf16 v[52:55], v[218:221], v[174:177], v[52:55]
	v_mfma_f32_16x16x32_bf16 v[44:47], v[226:229], v[174:177], v[44:47]
	v_mfma_f32_16x16x32_bf16 v[36:39], v[218:221], v[182:185], v[36:39]
	v_mfma_f32_16x16x32_bf16 v[28:31], v[226:229], v[182:185], v[28:31]
	v_mfma_f32_16x16x32_bf16 v[20:23], v[218:221], v[190:193], v[20:23]
	v_mfma_f32_16x16x32_bf16 v[12:15], v[226:229], v[190:193], v[12:15]
	v_mfma_f32_16x16x32_bf16 v[4:7], v[218:221], v[210:213], v[4:7]
	v_mfma_f32_16x16x32_bf16 v[0:3], v[226:229], v[210:213], v[0:3]
	v_mfma_f32_16x16x32_bf16 v[52:55], v[222:225], v[178:181], v[52:55]
	v_mfma_f32_16x16x32_bf16 v[44:47], v[230:233], v[178:181], v[44:47]
	v_mfma_f32_16x16x32_bf16 v[36:39], v[222:225], v[186:189], v[36:39]
	v_mfma_f32_16x16x32_bf16 v[28:31], v[230:233], v[186:189], v[28:31]
	v_mfma_f32_16x16x32_bf16 v[20:23], v[222:225], v[206:209], v[20:23]
	v_mfma_f32_16x16x32_bf16 v[12:15], v[230:233], v[206:209], v[12:15]
	v_mfma_f32_16x16x32_bf16 v[4:7], v[222:225], v[214:217], v[4:7]
	v_mfma_f32_16x16x32_bf16 v[0:3], v[230:233], v[214:217], v[0:3]
	s_barrier
	s_add_i32 s59, 0, 0x18000
	ds_read_b128 v[140:143], v236
	ds_read_b128 v[144:147], v236 offset:1024
	ds_read_b128 v[148:151], v236 offset:2048
	ds_read_b128 v[170:173], v236 offset:3072
	s_add_u32 s42, s42, 0x80000
	s_addc_u32 s43, s43, 0
	s_mov_b32 m0, s51
	ds_read_b128 v[174:177], v168 offset:32768
	ds_read_b128 v[178:181], v168 offset:33792
	ds_read_b128 v[182:185], v168 offset:34816
	ds_read_b128 v[186:189], v168 offset:35840
	ds_read_b128 v[190:193], v168 offset:36864
	ds_read_b128 v[206:209], v168 offset:37888
	ds_read_b128 v[210:213], v168 offset:38912
	ds_read_b128 v[214:217], v168 offset:39936
	global_load_lds_dwordx4 v128, s[42:43]
	s_mov_b32 m0, s52
	s_nop 0
	global_load_lds_dwordx4 v132, s[42:43]
	s_waitcnt lgkmcnt(8)
	s_barrier
	s_waitcnt lgkmcnt(0)
	v_mfma_f32_16x16x32_bf16 v[124:127], v[140:143], v[174:177], v[124:127]
	v_mfma_f32_16x16x32_bf16 v[120:123], v[148:151], v[174:177], v[120:123]
	v_mfma_f32_16x16x32_bf16 v[108:111], v[140:143], v[182:185], v[108:111]
	v_mfma_f32_16x16x32_bf16 v[104:107], v[148:151], v[182:185], v[104:107]
	v_mfma_f32_16x16x32_bf16 v[92:95], v[140:143], v[190:193], v[92:95]
	v_mfma_f32_16x16x32_bf16 v[88:91], v[148:151], v[190:193], v[88:91]
	v_mfma_f32_16x16x32_bf16 v[76:79], v[140:143], v[210:213], v[76:79]
	v_mfma_f32_16x16x32_bf16 v[72:75], v[148:151], v[210:213], v[72:75]
	v_mfma_f32_16x16x32_bf16 v[124:127], v[144:147], v[178:181], v[124:127]
	v_mfma_f32_16x16x32_bf16 v[120:123], v[170:173], v[178:181], v[120:123]
	v_mfma_f32_16x16x32_bf16 v[108:111], v[144:147], v[186:189], v[108:111]
	v_mfma_f32_16x16x32_bf16 v[104:107], v[170:173], v[186:189], v[104:107]
	v_mfma_f32_16x16x32_bf16 v[92:95], v[144:147], v[206:209], v[92:95]
	v_mfma_f32_16x16x32_bf16 v[88:91], v[170:173], v[206:209], v[88:91]
	v_mfma_f32_16x16x32_bf16 v[76:79], v[144:147], v[214:217], v[76:79]
	v_mfma_f32_16x16x32_bf16 v[72:75], v[170:173], v[214:217], v[72:75]
	s_barrier
	s_add_i32 s42, 0, 0x1c000
	s_add_i32 s43, s59, s48
	s_add_u32 s100, s22, 0x80
	s_addc_u32 s101, s23, 0
	s_mov_b32 m0, s43
	ds_read_b128 v[218:221], v237
	ds_read_b128 v[222:225], v237 offset:1024
	ds_read_b128 v[226:229], v237 offset:2048
	ds_read_b128 v[230:233], v237 offset:3072
	global_load_lds_dwordx4 v130, s[100:101]
	s_add_i32 m0, s43, 0x2000
	s_nop 0
	global_load_lds_dwordx4 v134, s[100:101]
	s_barrier
	s_waitcnt lgkmcnt(0)
	v_mfma_f32_16x16x32_bf16 v[116:119], v[218:221], v[174:177], v[116:119]
	v_mfma_f32_16x16x32_bf16 v[112:115], v[226:229], v[174:177], v[112:115]
	v_mfma_f32_16x16x32_bf16 v[100:103], v[218:221], v[182:185], v[100:103]
	v_mfma_f32_16x16x32_bf16 v[96:99], v[226:229], v[182:185], v[96:99]
	v_mfma_f32_16x16x32_bf16 v[84:87], v[218:221], v[190:193], v[84:87]
	v_mfma_f32_16x16x32_bf16 v[80:83], v[226:229], v[190:193], v[80:83]
	v_mfma_f32_16x16x32_bf16 v[68:71], v[218:221], v[210:213], v[68:71]
	v_mfma_f32_16x16x32_bf16 v[64:67], v[226:229], v[210:213], v[64:67]
	v_mfma_f32_16x16x32_bf16 v[116:119], v[222:225], v[178:181], v[116:119]
	v_mfma_f32_16x16x32_bf16 v[112:115], v[230:233], v[178:181], v[112:115]
	v_mfma_f32_16x16x32_bf16 v[100:103], v[222:225], v[186:189], v[100:103]
	v_mfma_f32_16x16x32_bf16 v[96:99], v[230:233], v[186:189], v[96:99]
	v_mfma_f32_16x16x32_bf16 v[84:87], v[222:225], v[206:209], v[84:87]
	v_mfma_f32_16x16x32_bf16 v[80:83], v[230:233], v[206:209], v[80:83]
	v_mfma_f32_16x16x32_bf16 v[68:71], v[222:225], v[214:217], v[68:71]
	v_mfma_f32_16x16x32_bf16 v[64:67], v[230:233], v[214:217], v[64:67]
	s_barrier
	s_mov_b32 m0, s53
	ds_read_b128 v[174:177], v168 offset:49152
	ds_read_b128 v[178:181], v168 offset:50176
	ds_read_b128 v[182:185], v168 offset:51200
	ds_read_b128 v[186:189], v168 offset:52224
	ds_read_b128 v[190:193], v168 offset:53248
	ds_read_b128 v[206:209], v168 offset:54272
	ds_read_b128 v[210:213], v168 offset:55296
	ds_read_b128 v[214:217], v168 offset:56320
	global_load_lds_dwordx4 v128, s[98:99]
	s_mov_b32 m0, s54
	s_nop 0
	global_load_lds_dwordx4 v132, s[98:99]
	s_barrier
	s_waitcnt lgkmcnt(0)
	v_mfma_f32_16x16x32_bf16 v[60:63], v[140:143], v[174:177], v[60:63]
	v_mfma_f32_16x16x32_bf16 v[56:59], v[148:151], v[174:177], v[56:59]
	v_mfma_f32_16x16x32_bf16 v[48:51], v[140:143], v[182:185], v[48:51]
	v_mfma_f32_16x16x32_bf16 v[40:43], v[148:151], v[182:185], v[40:43]
	v_mfma_f32_16x16x32_bf16 v[32:35], v[140:143], v[190:193], v[32:35]
	v_mfma_f32_16x16x32_bf16 v[24:27], v[148:151], v[190:193], v[24:27]
	v_mfma_f32_16x16x32_bf16 v[16:19], v[140:143], v[210:213], v[16:19]
	v_mfma_f32_16x16x32_bf16 v[8:11], v[148:151], v[210:213], v[8:11]
	v_mfma_f32_16x16x32_bf16 v[60:63], v[144:147], v[178:181], v[60:63]
	v_mfma_f32_16x16x32_bf16 v[56:59], v[170:173], v[178:181], v[56:59]
	v_mfma_f32_16x16x32_bf16 v[48:51], v[144:147], v[186:189], v[48:51]
	v_mfma_f32_16x16x32_bf16 v[40:43], v[170:173], v[186:189], v[40:43]
	v_mfma_f32_16x16x32_bf16 v[32:35], v[144:147], v[206:209], v[32:35]
	v_mfma_f32_16x16x32_bf16 v[24:27], v[170:173], v[206:209], v[24:27]
	v_mfma_f32_16x16x32_bf16 v[16:19], v[144:147], v[214:217], v[16:19]
	v_mfma_f32_16x16x32_bf16 v[8:11], v[170:173], v[214:217], v[8:11]
	s_barrier
	s_add_u32 s22, s22, 0x80080
	s_addc_u32 s23, s23, 0
	s_add_i32 s42, s42, s48
	s_mov_b32 m0, s42
	s_nop 0
	global_load_lds_dwordx4 v130, s[22:23]
	s_add_i32 m0, s42, 0x2000
	s_nop 0
	global_load_lds_dwordx4 v134, s[22:23]
	s_add_i32 s58, s58, 2
	s_add_u32 s20, s20, 0x100
	s_addc_u32 s21, s21, 0
	s_add_u32 s35, s35, 0x100
	s_addc_u32 s57, s57, 0
	s_cmp_gt_u32 s58, 29
	s_waitcnt vmcnt(6)
	s_barrier
	v_mfma_f32_16x16x32_bf16 v[52:55], v[218:221], v[174:177], v[52:55]
	v_mfma_f32_16x16x32_bf16 v[44:47], v[226:229], v[174:177], v[44:47]
	v_mfma_f32_16x16x32_bf16 v[36:39], v[218:221], v[182:185], v[36:39]
	v_mfma_f32_16x16x32_bf16 v[28:31], v[226:229], v[182:185], v[28:31]
	v_mfma_f32_16x16x32_bf16 v[20:23], v[218:221], v[190:193], v[20:23]
	v_mfma_f32_16x16x32_bf16 v[12:15], v[226:229], v[190:193], v[12:15]
	v_mfma_f32_16x16x32_bf16 v[4:7], v[218:221], v[210:213], v[4:7]
	v_mfma_f32_16x16x32_bf16 v[0:3], v[226:229], v[210:213], v[0:3]
	v_mfma_f32_16x16x32_bf16 v[52:55], v[222:225], v[178:181], v[52:55]
	v_mfma_f32_16x16x32_bf16 v[44:47], v[230:233], v[178:181], v[44:47]
	v_mfma_f32_16x16x32_bf16 v[36:39], v[222:225], v[186:189], v[36:39]
	v_mfma_f32_16x16x32_bf16 v[28:31], v[230:233], v[186:189], v[28:31]
	v_mfma_f32_16x16x32_bf16 v[20:23], v[222:225], v[206:209], v[20:23]
	v_mfma_f32_16x16x32_bf16 v[12:15], v[230:233], v[206:209], v[12:15]
	v_mfma_f32_16x16x32_bf16 v[4:7], v[222:225], v[214:217], v[4:7]
	v_mfma_f32_16x16x32_bf16 v[0:3], v[230:233], v[214:217], v[0:3]
	s_barrier
	s_cbranch_scc0 .LBB0_227
	v_lshl_add_u32 v140, s4, 8, v164
	s_cmp_gt_i32 s56, 23
	s_mov_b64 s[20:21], -1
	s_cbranch_scc1 .LBB0_262
	s_cmp_lt_i32 s56, 4
	s_cselect_b64 s[4:5], -1, 0
	s_and_b32 s6, s56, 0x7ffffffc
	s_cmp_eq_u32 s6, 16
	s_cselect_b64 s[6:7], -1, 0
	s_or_b64 s[20:21], s[4:5], s[6:7]
	s_and_b64 vcc, exec, s[20:21]
	v_mov_b32_e32 v149, v123
	v_mov_b32_e32 v148, v122
	v_mov_b32_e32 v163, v121
	v_mov_b32_e32 v162, v120
	v_mov_b32_e32 v147, v127
	v_mov_b32_e32 v146, v126
	v_mov_b32_e32 v151, v125
	v_mov_b32_e32 v150, v124
	s_cbranch_vccz .LBB0_231
	v_mul_f32_e32 v141, 0xbfb8aa3b, v124
	v_exp_f32_e32 v141, v141
	v_mul_f32_e32 v142, 0xbfb8aa3b, v120
	v_mul_f32_e32 v145, 0xbfb8aa3b, v126
	v_mul_f32_e32 v143, 0xbfb8aa3b, v125
	v_exp_f32_e32 v144, v142
	v_exp_f32_e32 v145, v145
	v_mul_f32_e32 v146, 0xbfb8aa3b, v122
	v_exp_f32_e32 v143, v143
	v_exp_f32_e32 v147, v146
	v_add_f32_e32 v141, 1.0, v141
	v_rcp_f32_e32 v142, v141
	v_add_f32_e32 v141, 1.0, v144
	v_add_f32_e32 v145, 1.0, v145
	v_rcp_f32_e32 v144, v141
	v_add_f32_e32 v141, 1.0, v143
	v_rcp_f32_e32 v146, v145
	v_add_f32_e32 v145, 1.0, v147
	v_mul_f32_e32 v147, 0xbfb8aa3b, v127
	v_rcp_f32_e32 v143, v141
	v_mul_f32_e32 v141, 0xbfb8aa3b, v121
	v_exp_f32_e32 v147, v147
	v_mul_f32_e32 v148, 0xbfb8aa3b, v123
	v_exp_f32_e32 v141, v141
	v_exp_f32_e32 v149, v148
	v_rcp_f32_e32 v148, v145
	v_add_f32_e32 v145, 1.0, v147
	v_add_f32_e32 v141, 1.0, v141
	v_rcp_f32_e32 v147, v145
	v_add_f32_e32 v145, 1.0, v149
	v_rcp_f32_e32 v149, v145
	v_rcp_f32_e32 v145, v141
	v_pk_mul_f32 v[146:147], v[126:127], v[146:147]
	v_pk_mul_f32 v[150:151], v[124:125], v[142:143]
	v_pk_mul_f32 v[148:149], v[122:123], v[148:149]
	v_pk_mul_f32 v[162:163], v[120:121], v[144:145]

.LBB0_561:
	s_add_u32 s38, s22, 0xfff80080
	s_addc_u32 s39, s23, -1
	s_add_i32 s84, 0, 0x10000
	ds_read_b128 v[72:75], v246
	ds_read_b128 v[76:79], v246 offset:1024
	ds_read_b128 v[84:87], v246 offset:2048
	ds_read_b128 v[92:95], v246 offset:3072
	s_cmp_eq_u32 s30, 28
	s_cselect_b32 s53, s5, s39
	s_cselect_b32 s52, s6, s38
	s_cselect_b32 s39, s1, s21
	s_cselect_b32 s38, s7, s17
	s_add_i32 m0, s61, 0xc000
	ds_read_b128 v[144:147], v208
	ds_read_b128 v[148:151], v208 offset:1024
	ds_read_b128 v[188:191], v208 offset:2048
	ds_read_b128 v[210:213], v208 offset:3072
	ds_read_b128 v[214:217], v208 offset:4096
	ds_read_b128 v[218:221], v208 offset:5120
	ds_read_b128 v[222:225], v208 offset:6144
	ds_read_b128 v[226:229], v208 offset:7168
	global_load_lds_dwordx4 v184, s[22:23]
	s_add_i32 m0, s61, 0xe000
	s_nop 0
	global_load_lds_dwordx4 v186, s[22:23]
	s_waitcnt lgkmcnt(8)
	s_barrier
	s_waitcnt lgkmcnt(0)
	v_mfma_f32_16x16x32_bf16 v[140:143], v[72:75], v[144:147], v[140:143]
	v_mfma_f32_16x16x32_bf16 v[136:139], v[84:87], v[144:147], v[136:139]
	v_mfma_f32_16x16x32_bf16 v[124:127], v[72:75], v[188:191], v[124:127]
	v_mfma_f32_16x16x32_bf16 v[120:123], v[84:87], v[188:191], v[120:123]
	v_mfma_f32_16x16x32_bf16 v[108:111], v[72:75], v[214:217], v[108:111]
	v_mfma_f32_16x16x32_bf16 v[104:107], v[84:87], v[214:217], v[104:107]
	v_mfma_f32_16x16x32_bf16 v[88:91], v[72:75], v[222:225], v[88:91]
	v_mfma_f32_16x16x32_bf16 v[80:83], v[84:87], v[222:225], v[80:83]
	v_mfma_f32_16x16x32_bf16 v[140:143], v[76:79], v[148:151], v[140:143]
	v_mfma_f32_16x16x32_bf16 v[136:139], v[92:95], v[148:151], v[136:139]
	v_mfma_f32_16x16x32_bf16 v[124:127], v[76:79], v[210:213], v[124:127]
	v_mfma_f32_16x16x32_bf16 v[120:123], v[92:95], v[210:213], v[120:123]
	v_mfma_f32_16x16x32_bf16 v[108:111], v[76:79], v[218:221], v[108:111]
	v_mfma_f32_16x16x32_bf16 v[104:107], v[92:95], v[218:221], v[104:107]
	v_mfma_f32_16x16x32_bf16 v[88:91], v[76:79], v[226:229], v[88:91]
	v_mfma_f32_16x16x32_bf16 v[80:83], v[92:95], v[226:229], v[80:83]
	s_barrier
	s_add_i32 s86, 0, 0x14000
	s_add_i32 s84, s84, s60
	ds_read_b128 v[230:233], v247
	ds_read_b128 v[234:237], v247 offset:1024
	ds_read_b128 v[238:241], v247 offset:2048
	ds_read_b128 v[242:245], v247 offset:3072
	s_mov_b32 m0, s84
	s_nop 0
	global_load_lds_dwordx4 v152, s[38:39]
	s_add_i32 m0, s84, 0x2000
	s_nop 0
	global_load_lds_dwordx4 v162, s[38:39]
	s_barrier
	s_waitcnt lgkmcnt(0)
	v_mfma_f32_16x16x32_bf16 v[132:135], v[230:233], v[144:147], v[132:135]
	v_mfma_f32_16x16x32_bf16 v[128:131], v[238:241], v[144:147], v[128:131]
	v_mfma_f32_16x16x32_bf16 v[116:119], v[230:233], v[188:191], v[116:119]
	v_mfma_f32_16x16x32_bf16 v[112:115], v[238:241], v[188:191], v[112:115]
	v_mfma_f32_16x16x32_bf16 v[100:103], v[230:233], v[214:217], v[100:103]
	v_mfma_f32_16x16x32_bf16 v[96:99], v[238:241], v[214:217], v[96:99]
	v_mfma_f32_16x16x32_bf16 v[68:71], v[230:233], v[222:225], v[68:71]
	v_mfma_f32_16x16x32_bf16 v[64:67], v[238:241], v[222:225], v[64:67]
	v_mfma_f32_16x16x32_bf16 v[132:135], v[234:237], v[148:151], v[132:135]
	v_mfma_f32_16x16x32_bf16 v[128:131], v[242:245], v[148:151], v[128:131]
	v_mfma_f32_16x16x32_bf16 v[116:119], v[234:237], v[210:213], v[116:119]
	v_mfma_f32_16x16x32_bf16 v[112:115], v[242:245], v[210:213], v[112:115]
	v_mfma_f32_16x16x32_bf16 v[100:103], v[234:237], v[218:221], v[100:103]
	v_mfma_f32_16x16x32_bf16 v[96:99], v[242:245], v[218:221], v[96:99]
	v_mfma_f32_16x16x32_bf16 v[68:71], v[234:237], v[226:229], v[68:71]
	v_mfma_f32_16x16x32_bf16 v[64:67], v[242:245], v[226:229], v[64:67]
	s_barrier
	s_mov_b32 m0, s61
	s_add_u32 s98, s52, 0x80
	s_addc_u32 s99, s53, 0
	ds_read_b128 v[144:147], v208 offset:16384
	ds_read_b128 v[148:151], v208 offset:17408
	ds_read_b128 v[188:191], v208 offset:18432
	ds_read_b128 v[210:213], v208 offset:19456
	ds_read_b128 v[214:217], v208 offset:20480
	ds_read_b128 v[218:221], v208 offset:21504
	ds_read_b128 v[222:225], v208 offset:22528
	ds_read_b128 v[226:229], v208 offset:23552
	global_load_lds_dwordx4 v166, s[52:53]
	s_mov_b32 m0, s62
	s_nop 0
	global_load_lds_dwordx4 v164, s[52:53]
	s_barrier
	s_waitcnt lgkmcnt(0)
	v_mfma_f32_16x16x32_bf16 v[60:63], v[72:75], v[144:147], v[60:63]
	v_mfma_f32_16x16x32_bf16 v[56:59], v[84:87], v[144:147], v[56:59]
	v_mfma_f32_16x16x32_bf16 v[44:47], v[72:75], v[188:191], v[44:47]
	v_mfma_f32_16x16x32_bf16 v[40:43], v[84:87], v[188:191], v[40:43]
	v_mfma_f32_16x16x32_bf16 v[28:31], v[72:75], v[214:217], v[28:31]
	v_mfma_f32_16x16x32_bf16 v[24:27], v[84:87], v[214:217], v[24:27]
	v_mfma_f32_16x16x32_bf16 v[12:15], v[72:75], v[222:225], v[12:15]
	v_mfma_f32_16x16x32_bf16 v[8:11], v[84:87], v[222:225], v[8:11]
	v_mfma_f32_16x16x32_bf16 v[60:63], v[76:79], v[148:151], v[60:63]
	v_mfma_f32_16x16x32_bf16 v[56:59], v[92:95], v[148:151], v[56:59]
	v_mfma_f32_16x16x32_bf16 v[44:47], v[76:79], v[210:213], v[44:47]
	v_mfma_f32_16x16x32_bf16 v[40:43], v[92:95], v[210:213], v[40:43]
	v_mfma_f32_16x16x32_bf16 v[28:31], v[76:79], v[218:221], v[28:31]
	v_mfma_f32_16x16x32_bf16 v[24:27], v[92:95], v[218:221], v[24:27]
	v_mfma_f32_16x16x32_bf16 v[12:15], v[76:79], v[226:229], v[12:15]
	v_mfma_f32_16x16x32_bf16 v[8:11], v[92:95], v[226:229], v[8:11]
	s_barrier
	s_add_u32 s84, s38, 0x80000
	s_addc_u32 s85, s39, 0
	s_add_i32 s86, s86, s60
	s_mov_b32 m0, s86
	s_nop 0
	global_load_lds_dwordx4 v152, s[84:85]
	s_add_i32 m0, s86, 0x2000
	s_nop 0
	global_load_lds_dwordx4 v162, s[84:85]
	s_waitcnt vmcnt(6)
	s_barrier
	v_mfma_f32_16x16x32_bf16 v[52:55], v[230:233], v[144:147], v[52:55]
	v_mfma_f32_16x16x32_bf16 v[48:51], v[238:241], v[144:147], v[48:51]
	v_mfma_f32_16x16x32_bf16 v[36:39], v[230:233], v[188:191], v[36:39]
	v_mfma_f32_16x16x32_bf16 v[32:35], v[238:241], v[188:191], v[32:35]
	v_mfma_f32_16x16x32_bf16 v[20:23], v[230:233], v[214:217], v[20:23]
	v_mfma_f32_16x16x32_bf16 v[16:19], v[238:241], v[214:217], v[16:19]
	v_mfma_f32_16x16x32_bf16 v[4:7], v[230:233], v[222:225], v[4:7]
	v_mfma_f32_16x16x32_bf16 v[0:3], v[238:241], v[222:225], v[0:3]
	v_mfma_f32_16x16x32_bf16 v[52:55], v[234:237], v[148:151], v[52:55]
	v_mfma_f32_16x16x32_bf16 v[48:51], v[242:245], v[148:151], v[48:51]
	v_mfma_f32_16x16x32_bf16 v[36:39], v[234:237], v[210:213], v[36:39]
	v_mfma_f32_16x16x32_bf16 v[32:35], v[242:245], v[210:213], v[32:35]
	v_mfma_f32_16x16x32_bf16 v[20:23], v[234:237], v[218:221], v[20:23]
	v_mfma_f32_16x16x32_bf16 v[16:19], v[242:245], v[218:221], v[16:19]
	v_mfma_f32_16x16x32_bf16 v[4:7], v[234:237], v[226:229], v[4:7]
	v_mfma_f32_16x16x32_bf16 v[0:3], v[242:245], v[226:229], v[0:3]
	s_barrier
	s_add_i32 s84, 0, 0x18000
	ds_read_b128 v[72:75], v248
	ds_read_b128 v[76:79], v248 offset:1024
	ds_read_b128 v[84:87], v248 offset:2048
	ds_read_b128 v[92:95], v248 offset:3072
	s_add_u32 s52, s52, 0x80000
	s_addc_u32 s53, s53, 0
	s_mov_b32 m0, s63
	ds_read_b128 v[144:147], v208 offset:32768
	ds_read_b128 v[148:151], v208 offset:33792
	ds_read_b128 v[188:191], v208 offset:34816
	ds_read_b128 v[210:213], v208 offset:35840
	ds_read_b128 v[214:217], v208 offset:36864
	ds_read_b128 v[218:221], v208 offset:37888
	ds_read_b128 v[222:225], v208 offset:38912
	ds_read_b128 v[226:229], v208 offset:39936
	global_load_lds_dwordx4 v166, s[52:53]
	s_mov_b32 m0, s68
	s_nop 0
	global_load_lds_dwordx4 v164, s[52:53]
	s_waitcnt lgkmcnt(8)
	s_barrier
	s_waitcnt lgkmcnt(0)
	v_mfma_f32_16x16x32_bf16 v[140:143], v[72:75], v[144:147], v[140:143]
	v_mfma_f32_16x16x32_bf16 v[136:139], v[84:87], v[144:147], v[136:139]
	v_mfma_f32_16x16x32_bf16 v[124:127], v[72:75], v[188:191], v[124:127]
	v_mfma_f32_16x16x32_bf16 v[120:123], v[84:87], v[188:191], v[120:123]
	v_mfma_f32_16x16x32_bf16 v[108:111], v[72:75], v[214:217], v[108:111]
	v_mfma_f32_16x16x32_bf16 v[104:107], v[84:87], v[214:217], v[104:107]
	v_mfma_f32_16x16x32_bf16 v[88:91], v[72:75], v[222:225], v[88:91]
	v_mfma_f32_16x16x32_bf16 v[80:83], v[84:87], v[222:225], v[80:83]
	v_mfma_f32_16x16x32_bf16 v[140:143], v[76:79], v[148:151], v[140:143]
	v_mfma_f32_16x16x32_bf16 v[136:139], v[92:95], v[148:151], v[136:139]
	v_mfma_f32_16x16x32_bf16 v[124:127], v[76:79], v[210:213], v[124:127]
	v_mfma_f32_16x16x32_bf16 v[120:123], v[92:95], v[210:213], v[120:123]
	v_mfma_f32_16x16x32_bf16 v[108:111], v[76:79], v[218:221], v[108:111]
	v_mfma_f32_16x16x32_bf16 v[104:107], v[92:95], v[218:221], v[104:107]
	v_mfma_f32_16x16x32_bf16 v[88:91], v[76:79], v[226:229], v[88:91]
	v_mfma_f32_16x16x32_bf16 v[80:83], v[92:95], v[226:229], v[80:83]
	s_barrier
	s_add_i32 s52, 0, 0x1c000
	s_add_i32 s53, s84, s60
	s_add_u32 s100, s38, 0x80
	s_addc_u32 s101, s39, 0
	s_mov_b32 m0, s53
	ds_read_b128 v[230:233], v249
	ds_read_b128 v[234:237], v249 offset:1024
	ds_read_b128 v[238:241], v249 offset:2048
	ds_read_b128 v[242:245], v249 offset:3072
	global_load_lds_dwordx4 v152, s[100:101]
	s_add_i32 m0, s53, 0x2000
	s_nop 0
	global_load_lds_dwordx4 v162, s[100:101]
	s_barrier
	s_waitcnt lgkmcnt(0)
	v_mfma_f32_16x16x32_bf16 v[132:135], v[230:233], v[144:147], v[132:135]
	v_mfma_f32_16x16x32_bf16 v[128:131], v[238:241], v[144:147], v[128:131]
	v_mfma_f32_16x16x32_bf16 v[116:119], v[230:233], v[188:191], v[116:119]
	v_mfma_f32_16x16x32_bf16 v[112:115], v[238:241], v[188:191], v[112:115]
	v_mfma_f32_16x16x32_bf16 v[100:103], v[230:233], v[214:217], v[100:103]
	v_mfma_f32_16x16x32_bf16 v[96:99], v[238:241], v[214:217], v[96:99]
	v_mfma_f32_16x16x32_bf16 v[68:71], v[230:233], v[222:225], v[68:71]
	v_mfma_f32_16x16x32_bf16 v[64:67], v[238:241], v[222:225], v[64:67]
	v_mfma_f32_16x16x32_bf16 v[132:135], v[234:237], v[148:151], v[132:135]
	v_mfma_f32_16x16x32_bf16 v[128:131], v[242:245], v[148:151], v[128:131]
	v_mfma_f32_16x16x32_bf16 v[116:119], v[234:237], v[210:213], v[116:119]
	v_mfma_f32_16x16x32_bf16 v[112:115], v[242:245], v[210:213], v[112:115]
	v_mfma_f32_16x16x32_bf16 v[100:103], v[234:237], v[218:221], v[100:103]
	v_mfma_f32_16x16x32_bf16 v[96:99], v[242:245], v[218:221], v[96:99]
	v_mfma_f32_16x16x32_bf16 v[68:71], v[234:237], v[226:229], v[68:71]
	v_mfma_f32_16x16x32_bf16 v[64:67], v[242:245], v[226:229], v[64:67]
	s_barrier
	s_mov_b32 m0, s81
	ds_read_b128 v[144:147], v208 offset:49152
	ds_read_b128 v[148:151], v208 offset:50176
	ds_read_b128 v[188:191], v208 offset:51200
	ds_read_b128 v[210:213], v208 offset:52224
	ds_read_b128 v[214:217], v208 offset:53248
	ds_read_b128 v[218:221], v208 offset:54272
	ds_read_b128 v[222:225], v208 offset:55296
	ds_read_b128 v[226:229], v208 offset:56320
	global_load_lds_dwordx4 v166, s[98:99]
	s_mov_b32 m0, s82
	s_nop 0
	global_load_lds_dwordx4 v164, s[98:99]
	s_barrier
	s_waitcnt lgkmcnt(0)
	v_mfma_f32_16x16x32_bf16 v[60:63], v[72:75], v[144:147], v[60:63]
	v_mfma_f32_16x16x32_bf16 v[56:59], v[84:87], v[144:147], v[56:59]
	v_mfma_f32_16x16x32_bf16 v[44:47], v[72:75], v[188:191], v[44:47]
	v_mfma_f32_16x16x32_bf16 v[40:43], v[84:87], v[188:191], v[40:43]
	v_mfma_f32_16x16x32_bf16 v[28:31], v[72:75], v[214:217], v[28:31]
	v_mfma_f32_16x16x32_bf16 v[24:27], v[84:87], v[214:217], v[24:27]
	v_mfma_f32_16x16x32_bf16 v[12:15], v[72:75], v[222:225], v[12:15]
	v_mfma_f32_16x16x32_bf16 v[8:11], v[84:87], v[222:225], v[8:11]
	v_mfma_f32_16x16x32_bf16 v[60:63], v[76:79], v[148:151], v[60:63]
	v_mfma_f32_16x16x32_bf16 v[56:59], v[92:95], v[148:151], v[56:59]
	v_mfma_f32_16x16x32_bf16 v[44:47], v[76:79], v[210:213], v[44:47]
	v_mfma_f32_16x16x32_bf16 v[40:43], v[92:95], v[210:213], v[40:43]
	v_mfma_f32_16x16x32_bf16 v[28:31], v[76:79], v[218:221], v[28:31]
	v_mfma_f32_16x16x32_bf16 v[24:27], v[92:95], v[218:221], v[24:27]
	v_mfma_f32_16x16x32_bf16 v[12:15], v[76:79], v[226:229], v[12:15]
	v_mfma_f32_16x16x32_bf16 v[8:11], v[92:95], v[226:229], v[8:11]
	s_barrier
	s_add_u32 s38, s38, 0x80080
	s_addc_u32 s39, s39, 0
	s_add_i32 s52, s52, s60
	s_mov_b32 m0, s52
	s_nop 0
	global_load_lds_dwordx4 v152, s[38:39]
	s_add_i32 m0, s52, 0x2000
	s_nop 0
	global_load_lds_dwordx4 v162, s[38:39]
	s_add_i32 s30, s30, 2
	s_add_u32 s22, s22, 0x100
	s_addc_u32 s23, s23, 0
	s_add_u32 s17, s17, 0x100
	s_addc_u32 s21, s21, 0
	s_cmp_gt_u32 s30, 29
	s_waitcnt vmcnt(6)
	s_barrier
	v_mfma_f32_16x16x32_bf16 v[52:55], v[230:233], v[144:147], v[52:55]
	v_mfma_f32_16x16x32_bf16 v[48:51], v[238:241], v[144:147], v[48:51]
	v_mfma_f32_16x16x32_bf16 v[36:39], v[230:233], v[188:191], v[36:39]
	v_mfma_f32_16x16x32_bf16 v[32:35], v[238:241], v[188:191], v[32:35]
	v_mfma_f32_16x16x32_bf16 v[20:23], v[230:233], v[214:217], v[20:23]
	v_mfma_f32_16x16x32_bf16 v[16:19], v[238:241], v[214:217], v[16:19]
	v_mfma_f32_16x16x32_bf16 v[4:7], v[230:233], v[222:225], v[4:7]
	v_mfma_f32_16x16x32_bf16 v[0:3], v[238:241], v[222:225], v[0:3]
	v_mfma_f32_16x16x32_bf16 v[52:55], v[234:237], v[148:151], v[52:55]
	v_mfma_f32_16x16x32_bf16 v[48:51], v[242:245], v[148:151], v[48:51]
	v_mfma_f32_16x16x32_bf16 v[36:39], v[234:237], v[210:213], v[36:39]
	v_mfma_f32_16x16x32_bf16 v[32:35], v[242:245], v[210:213], v[32:35]
	v_mfma_f32_16x16x32_bf16 v[20:23], v[234:237], v[218:221], v[20:23]
	v_mfma_f32_16x16x32_bf16 v[16:19], v[242:245], v[218:221], v[16:19]
	v_mfma_f32_16x16x32_bf16 v[4:7], v[234:237], v[226:229], v[4:7]
	v_mfma_f32_16x16x32_bf16 v[0:3], v[242:245], v[226:229], v[0:3]
	s_barrier
	s_cbranch_scc0 .LBB0_561
	v_lshl_or_b32 v188, s4, 8, v207
	v_ashrrev_i32_e32 v189, 31, v188
	s_cmp_lt_i32 s20, 16
	s_cselect_b32 s6, s44, s46
	s_cselect_b32 s7, s45, s47
	s_cselect_b32 s1, 0, 16
	s_sub_i32 s4, s20, s1
	s_mov_b32 s5, 0
	s_lshl_b64 s[4:5], s[4:5], 21
	s_add_u32 s38, s6, s4
	s_addc_u32 s39, s7, s5
	s_cmp_lt_i32 s20, 32
	s_cselect_b32 s1, 0x3000, s73
	s_cmp_lt_i32 s20, 16
	s_cselect_b32 s1, 0, s1
	s_lshl_b32 s1, s1, 2
	s_add_u32 s6, s79, s1
	s_addc_u32 s7, s80, 0
	s_mov_b32 s4, s20
	s_mov_b32 s5, 0
	s_lshl_b64 s[4:5], s[4:5], 20
	s_add_u32 s52, s69, s4
	s_addc_u32 s53, s78, s5
	v_lshl_add_u64 v[190:191], v[188:189], 2, s[6:7]
	s_mov_b64 s[4:5], 0x28504000
	v_lshl_add_u64 v[190:191], v[190:191], 0, s[4:5]
	global_load_dwordx4 v[92:95], v[190:191], off
	global_load_dwordx4 v[84:87], v[190:191], off offset:16
	global_load_dwordx4 v[76:79], v[190:191], off offset:512
	global_load_dwordx4 v[72:75], v[190:191], off offset:528
	v_lshl_add_u64 v[144:145], v[188:189], 1, s[52:53]
	s_and_b64 vcc, exec, s[64:65]
	s_cbranch_vccz .Lwo_epi_f32
	v_lshl_add_u64 v[148:149], v[168:169], 1, v[144:145]
	global_load_dwordx4 v[210:213], v[148:149], off
	global_load_dwordx4 v[214:217], v[148:149], off offset:256
	v_lshl_add_u64 v[148:149], v[170:171], 1, v[144:145]
	global_load_dwordx4 v[218:221], v[148:149], off
	global_load_dwordx4 v[222:225], v[148:149], off offset:256
	v_lshl_add_u64 v[148:149], v[172:173], 1, v[144:145]
	global_load_dwordx4 v[226:229], v[148:149], off
	global_load_dwordx4 v[230:233], v[148:149], off offset:256
	v_lshl_add_u64 v[148:149], v[174:175], 1, v[144:145]
	global_load_dwordx4 v[234:237], v[148:149], off
	global_load_dwordx4 v[238:241], v[148:149], off offset:256
	v_lshl_add_u64 v[148:149], v[176:177], 1, v[144:145]
	global_load_dwordx4 v[242:245], v[148:149], off
	s_waitcnt vmcnt(8)
	v_lshlrev_b32_e32 v188, 16, v210
	v_and_b32_e32 v189, 0xffff0000, v210
	v_lshlrev_b32_e32 v190, 16, v211
	v_and_b32_e32 v191, 0xffff0000, v211
	v_lshlrev_b32_e32 v246, 16, v212
	v_and_b32_e32 v247, 0xffff0000, v212
	v_lshlrev_b32_e32 v248, 16, v213
	v_and_b32_e32 v249, 0xffff0000, v213
	global_load_dwordx4 v[210:213], v[148:149], off offset:256
	v_lshl_add_u64 v[150:151], v[168:169], 1, v[144:145]
	v_pk_fma_f32 v[140:141], v[140:141], v[92:93], v[188:189]
	v_pk_fma_f32 v[142:143], v[142:143], v[94:95], v[190:191]
	v_pk_fma_f32 v[136:137], v[136:137], v[84:85], v[246:247]
	v_pk_fma_f32 v[138:139], v[138:139], v[86:87], v[248:249]
	v_cvt_pk_bf16_f32 v140, v140, v141
	v_cvt_pk_bf16_f32 v141, v142, v143
	v_cvt_pk_bf16_f32 v142, v136, v137
	v_cvt_pk_bf16_f32 v143, v138, v139
	global_store_dwordx4 v[150:151], v[140:143], off
	s_waitcnt vmcnt(9)
	v_lshlrev_b32_e32 v188, 16, v214
	v_and_b32_e32 v189, 0xffff0000, v214
	v_lshlrev_b32_e32 v190, 16, v215
	v_and_b32_e32 v191, 0xffff0000, v215
	v_lshlrev_b32_e32 v246, 16, v216
	v_and_b32_e32 v247, 0xffff0000, v216
	v_lshlrev_b32_e32 v248, 16, v217
	v_and_b32_e32 v249, 0xffff0000, v217
	v_lshl_add_u64 v[148:149], v[178:179], 1, v[144:145]
	global_load_dwordx4 v[214:217], v[148:149], off
	v_pk_fma_f32 v[132:133], v[132:133], v[76:77], v[188:189]
	v_pk_fma_f32 v[134:135], v[134:135], v[78:79], v[190:191]
	v_pk_fma_f32 v[128:129], v[128:129], v[72:73], v[246:247]
	v_pk_fma_f32 v[130:131], v[130:131], v[74:75], v[248:249]
	v_cvt_pk_bf16_f32 v132, v132, v133
	v_cvt_pk_bf16_f32 v133, v134, v135
	v_cvt_pk_bf16_f32 v134, v128, v129
	v_cvt_pk_bf16_f32 v135, v130, v131
	global_store_dwordx4 v[150:151], v[132:135], off offset:256
	s_waitcnt vmcnt(10)
	v_lshlrev_b32_e32 v188, 16, v218
	v_and_b32_e32 v189, 0xffff0000, v218
	v_lshlrev_b32_e32 v190, 16, v219
	v_and_b32_e32 v191, 0xffff0000, v219
	v_lshlrev_b32_e32 v246, 16, v220
	v_and_b32_e32 v247, 0xffff0000, v220
	v_lshlrev_b32_e32 v248, 16, v221
	v_and_b32_e32 v249, 0xffff0000, v221
	global_load_dwordx4 v[218:221], v[148:149], off offset:256
	v_lshl_add_u64 v[192:193], v[170:171], 1, v[144:145]
	v_pk_fma_f32 v[124:125], v[124:125], v[92:93], v[188:189]
	v_pk_fma_f32 v[126:127], v[126:127], v[94:95], v[190:191]
	v_pk_fma_f32 v[120:121], v[120:121], v[84:85], v[246:247]
	v_pk_fma_f32 v[122:123], v[122:123], v[86:87], v[248:249]
	v_cvt_pk_bf16_f32 v124, v124, v125
	v_cvt_pk_bf16_f32 v125, v126, v127
	v_cvt_pk_bf16_f32 v126, v120, v121
	v_cvt_pk_bf16_f32 v127, v122, v123
	global_store_dwordx4 v[192:193], v[124:127], off
	s_waitcnt vmcnt(11)
	v_lshlrev_b32_e32 v188, 16, v222
	v_and_b32_e32 v189, 0xffff0000, v222
	v_lshlrev_b32_e32 v190, 16, v223
	v_and_b32_e32 v191, 0xffff0000, v223
	v_lshlrev_b32_e32 v246, 16, v224
	v_and_b32_e32 v247, 0xffff0000, v224
	v_lshlrev_b32_e32 v248, 16, v225
	v_and_b32_e32 v249, 0xffff0000, v225
	v_lshl_add_u64 v[148:149], v[180:181], 1, v[144:145]
	global_load_dwordx4 v[222:225], v[148:149], off
	v_pk_fma_f32 v[116:117], v[116:117], v[76:77], v[188:189]
	v_pk_fma_f32 v[118:119], v[118:119], v[78:79], v[190:191]
	v_pk_fma_f32 v[112:113], v[112:113], v[72:73], v[246:247]
	v_pk_fma_f32 v[114:115], v[114:115], v[74:75], v[248:249]
	v_cvt_pk_bf16_f32 v116, v116, v117
	v_cvt_pk_bf16_f32 v117, v118, v119
	v_cvt_pk_bf16_f32 v118, v112, v113
	v_cvt_pk_bf16_f32 v119, v114, v115
	global_store_dwordx4 v[192:193], v[116:119], off offset:256
	s_waitcnt vmcnt(12)
	v_lshlrev_b32_e32 v188, 16, v226
	v_and_b32_e32 v189, 0xffff0000, v226
	v_lshlrev_b32_e32 v190, 16, v227
	v_and_b32_e32 v191, 0xffff0000, v227
	v_lshlrev_b32_e32 v246, 16, v228
	v_and_b32_e32 v247, 0xffff0000, v228
	v_lshlrev_b32_e32 v248, 16, v229
	v_and_b32_e32 v249, 0xffff0000, v229
	global_load_dwordx4 v[226:229], v[148:149], off offset:256
	v_lshl_add_u64 v[150:151], v[172:173], 1, v[144:145]
	v_pk_fma_f32 v[108:109], v[108:109], v[92:93], v[188:189]
	v_pk_fma_f32 v[110:111], v[110:111], v[94:95], v[190:191]
	v_pk_fma_f32 v[104:105], v[104:105], v[84:85], v[246:247]
	v_pk_fma_f32 v[106:107], v[106:107], v[86:87], v[248:249]
	v_cvt_pk_bf16_f32 v108, v108, v109
	v_cvt_pk_bf16_f32 v109, v110, v111
	v_cvt_pk_bf16_f32 v110, v104, v105
	v_cvt_pk_bf16_f32 v111, v106, v107
	global_store_dwordx4 v[150:151], v[108:111], off
	s_waitcnt vmcnt(13)
	v_lshlrev_b32_e32 v188, 16, v230
	v_and_b32_e32 v189, 0xffff0000, v230
	v_lshlrev_b32_e32 v190, 16, v231
	v_and_b32_e32 v191, 0xffff0000, v231
	v_lshlrev_b32_e32 v246, 16, v232
	v_and_b32_e32 v247, 0xffff0000, v232
	v_lshlrev_b32_e32 v248, 16, v233
	v_and_b32_e32 v249, 0xffff0000, v233
	v_lshl_add_u64 v[148:149], v[182:183], 1, v[144:145]
	global_load_dwordx4 v[230:233], v[148:149], off
	v_pk_fma_f32 v[100:101], v[100:101], v[76:77], v[188:189]
	v_pk_fma_f32 v[102:103], v[102:103], v[78:79], v[190:191]
	v_pk_fma_f32 v[96:97], v[96:97], v[72:73], v[246:247]
	v_pk_fma_f32 v[98:99], v[98:99], v[74:75], v[248:249]
	v_cvt_pk_bf16_f32 v100, v100, v101
	v_cvt_pk_bf16_f32 v101, v102, v103
	v_cvt_pk_bf16_f32 v102, v96, v97
	v_cvt_pk_bf16_f32 v103, v98, v99
	global_store_dwordx4 v[150:151], v[100:103], off offset:256
	s_waitcnt vmcnt(14)
	v_lshlrev_b32_e32 v188, 16, v234
	v_and_b32_e32 v189, 0xffff0000, v234
	v_lshlrev_b32_e32 v190, 16, v235
	v_and_b32_e32 v191, 0xffff0000, v235
	v_lshlrev_b32_e32 v246, 16, v236
	v_and_b32_e32 v247, 0xffff0000, v236
	v_lshlrev_b32_e32 v248, 16, v237
	v_and_b32_e32 v249, 0xffff0000, v237
	global_load_dwordx4 v[234:237], v[148:149], off offset:256
	v_lshl_add_u64 v[192:193], v[174:175], 1, v[144:145]
	v_pk_fma_f32 v[88:89], v[88:89], v[92:93], v[188:189]
	v_pk_fma_f32 v[90:91], v[90:91], v[94:95], v[190:191]
	v_pk_fma_f32 v[80:81], v[80:81], v[84:85], v[246:247]
	v_pk_fma_f32 v[82:83], v[82:83], v[86:87], v[248:249]
	v_cvt_pk_bf16_f32 v88, v88, v89
	v_cvt_pk_bf16_f32 v89, v90, v91
	v_cvt_pk_bf16_f32 v90, v80, v81
	v_cvt_pk_bf16_f32 v91, v82, v83
	global_store_dwordx4 v[192:193], v[88:91], off
	s_waitcnt vmcnt(15)
	v_lshlrev_b32_e32 v188, 16, v238
	v_and_b32_e32 v189, 0xffff0000, v238
	v_lshlrev_b32_e32 v190, 16, v239
	v_and_b32_e32 v191, 0xffff0000, v239
	v_lshlrev_b32_e32 v246, 16, v240
	v_and_b32_e32 v247, 0xffff0000, v240
	v_lshlrev_b32_e32 v248, 16, v241
	v_and_b32_e32 v249, 0xffff0000, v241
	v_pk_fma_f32 v[68:69], v[68:69], v[76:77], v[188:189]
	v_pk_fma_f32 v[70:71], v[70:71], v[78:79], v[190:191]
	v_pk_fma_f32 v[64:65], v[64:65], v[72:73], v[246:247]
	v_pk_fma_f32 v[66:67], v[66:67], v[74:75], v[248:249]
	v_cvt_pk_bf16_f32 v68, v68, v69
	v_cvt_pk_bf16_f32 v69, v70, v71
	v_cvt_pk_bf16_f32 v70, v64, v65
	v_cvt_pk_bf16_f32 v71, v66, v67
	global_store_dwordx4 v[192:193], v[68:71], off offset:256
	s_waitcnt vmcnt(15)
	v_lshlrev_b32_e32 v188, 16, v242
	v_and_b32_e32 v189, 0xffff0000, v242
	v_lshlrev_b32_e32 v190, 16, v243
	v_and_b32_e32 v191, 0xffff0000, v243
	v_lshlrev_b32_e32 v246, 16, v244
	v_and_b32_e32 v247, 0xffff0000, v244
	v_lshlrev_b32_e32 v248, 16, v245
	v_and_b32_e32 v249, 0xffff0000, v245
	v_lshl_add_u64 v[150:151], v[176:177], 1, v[144:145]
	v_pk_fma_f32 v[60:61], v[60:61], v[92:93], v[188:189]
	v_pk_fma_f32 v[62:63], v[62:63], v[94:95], v[190:191]
	v_pk_fma_f32 v[56:57], v[56:57], v[84:85], v[246:247]
	v_pk_fma_f32 v[58:59], v[58:59], v[86:87], v[248:249]
	v_cvt_pk_bf16_f32 v60, v60, v61
	v_cvt_pk_bf16_f32 v61, v62, v63
	v_cvt_pk_bf16_f32 v62, v56, v57
	v_cvt_pk_bf16_f32 v63, v58, v59
	global_store_dwordx4 v[150:151], v[60:63], off
	s_waitcnt vmcnt(15)
	v_lshlrev_b32_e32 v188, 16, v210
	v_and_b32_e32 v189, 0xffff0000, v210
	v_lshlrev_b32_e32 v190, 16, v211
	v_and_b32_e32 v191, 0xffff0000, v211
	v_lshlrev_b32_e32 v246, 16, v212
	v_and_b32_e32 v247, 0xffff0000, v212
	v_lshlrev_b32_e32 v248, 16, v213
	v_and_b32_e32 v249, 0xffff0000, v213
	v_pk_fma_f32 v[52:53], v[52:53], v[76:77], v[188:189]
	v_pk_fma_f32 v[54:55], v[54:55], v[78:79], v[190:191]
	v_pk_fma_f32 v[48:49], v[48:49], v[72:73], v[246:247]
	v_pk_fma_f32 v[50:51], v[50:51], v[74:75], v[248:249]
	v_cvt_pk_bf16_f32 v52, v52, v53
	v_cvt_pk_bf16_f32 v53, v54, v55
	v_cvt_pk_bf16_f32 v54, v48, v49
	v_cvt_pk_bf16_f32 v55, v50, v51
	global_store_dwordx4 v[150:151], v[52:55], off offset:256
	s_waitcnt vmcnt(14)
	v_lshlrev_b32_e32 v188, 16, v214
	v_and_b32_e32 v189, 0xffff0000, v214
	v_lshlrev_b32_e32 v190, 16, v215
	v_and_b32_e32 v191, 0xffff0000, v215
	v_lshlrev_b32_e32 v246, 16, v216
	v_and_b32_e32 v247, 0xffff0000, v216
	v_lshlrev_b32_e32 v248, 16, v217
	v_and_b32_e32 v249, 0xffff0000, v217
	v_lshl_add_u64 v[192:193], v[178:179], 1, v[144:145]
	v_pk_fma_f32 v[44:45], v[44:45], v[92:93], v[188:189]
	v_pk_fma_f32 v[46:47], v[46:47], v[94:95], v[190:191]
	v_pk_fma_f32 v[40:41], v[40:41], v[84:85], v[246:247]
	v_pk_fma_f32 v[42:43], v[42:43], v[86:87], v[248:249]
	v_cvt_pk_bf16_f32 v44, v44, v45
	v_cvt_pk_bf16_f32 v45, v46, v47
	v_cvt_pk_bf16_f32 v46, v40, v41
	v_cvt_pk_bf16_f32 v47, v42, v43
	global_store_dwordx4 v[192:193], v[44:47], off
	s_waitcnt vmcnt(13)
	v_lshlrev_b32_e32 v188, 16, v218
	v_and_b32_e32 v189, 0xffff0000, v218
	v_lshlrev_b32_e32 v190, 16, v219
	v_and_b32_e32 v191, 0xffff0000, v219
	v_lshlrev_b32_e32 v246, 16, v220
	v_and_b32_e32 v247, 0xffff0000, v220
	v_lshlrev_b32_e32 v248, 16, v221
	v_and_b32_e32 v249, 0xffff0000, v221
	v_pk_fma_f32 v[36:37], v[36:37], v[76:77], v[188:189]
	v_pk_fma_f32 v[38:39], v[38:39], v[78:79], v[190:191]
	v_pk_fma_f32 v[32:33], v[32:33], v[72:73], v[246:247]
	v_pk_fma_f32 v[34:35], v[34:35], v[74:75], v[248:249]
	v_cvt_pk_bf16_f32 v36, v36, v37
	v_cvt_pk_bf16_f32 v37, v38, v39
	v_cvt_pk_bf16_f32 v38, v32, v33
	v_cvt_pk_bf16_f32 v39, v34, v35
	global_store_dwordx4 v[192:193], v[36:39], off offset:256
	s_waitcnt vmcnt(12)
	v_lshlrev_b32_e32 v188, 16, v222
	v_and_b32_e32 v189, 0xffff0000, v222
	v_lshlrev_b32_e32 v190, 16, v223
	v_and_b32_e32 v191, 0xffff0000, v223
	v_lshlrev_b32_e32 v246, 16, v224
	v_and_b32_e32 v247, 0xffff0000, v224
	v_lshlrev_b32_e32 v248, 16, v225
	v_and_b32_e32 v249, 0xffff0000, v225
	v_lshl_add_u64 v[150:151], v[180:181], 1, v[144:145]
	v_pk_fma_f32 v[28:29], v[28:29], v[92:93], v[188:189]
	v_pk_fma_f32 v[30:31], v[30:31], v[94:95], v[190:191]
	v_pk_fma_f32 v[24:25], v[24:25], v[84:85], v[246:247]
	v_pk_fma_f32 v[26:27], v[26:27], v[86:87], v[248:249]
	v_cvt_pk_bf16_f32 v28, v28, v29
	v_cvt_pk_bf16_f32 v29, v30, v31
	v_cvt_pk_bf16_f32 v30, v24, v25
	v_cvt_pk_bf16_f32 v31, v26, v27
	global_store_dwordx4 v[150:151], v[28:31], off
	s_waitcnt vmcnt(11)
	v_lshlrev_b32_e32 v188, 16, v226
	v_and_b32_e32 v189, 0xffff0000, v226
	v_lshlrev_b32_e32 v190, 16, v227
	v_and_b32_e32 v191, 0xffff0000, v227
	v_lshlrev_b32_e32 v246, 16, v228
	v_and_b32_e32 v247, 0xffff0000, v228
	v_lshlrev_b32_e32 v248, 16, v229
	v_and_b32_e32 v249, 0xffff0000, v229
	v_pk_fma_f32 v[20:21], v[20:21], v[76:77], v[188:189]
	v_pk_fma_f32 v[22:23], v[22:23], v[78:79], v[190:191]
	v_pk_fma_f32 v[16:17], v[16:17], v[72:73], v[246:247]
	v_pk_fma_f32 v[18:19], v[18:19], v[74:75], v[248:249]
	v_cvt_pk_bf16_f32 v20, v20, v21
	v_cvt_pk_bf16_f32 v21, v22, v23
	v_cvt_pk_bf16_f32 v22, v16, v17
	v_cvt_pk_bf16_f32 v23, v18, v19
	global_store_dwordx4 v[150:151], v[20:23], off offset:256
	s_waitcnt vmcnt(10)
	v_lshlrev_b32_e32 v188, 16, v230
	v_and_b32_e32 v189, 0xffff0000, v230
	v_lshlrev_b32_e32 v190, 16, v231
	v_and_b32_e32 v191, 0xffff0000, v231
	v_lshlrev_b32_e32 v246, 16, v232
	v_and_b32_e32 v247, 0xffff0000, v232
	v_lshlrev_b32_e32 v248, 16, v233
	v_and_b32_e32 v249, 0xffff0000, v233
	v_lshl_add_u64 v[192:193], v[182:183], 1, v[144:145]
	v_pk_fma_f32 v[12:13], v[12:13], v[92:93], v[188:189]
	v_pk_fma_f32 v[14:15], v[14:15], v[94:95], v[190:191]
	v_pk_fma_f32 v[8:9], v[8:9], v[84:85], v[246:247]
	v_pk_fma_f32 v[10:11], v[10:11], v[86:87], v[248:249]
	v_cvt_pk_bf16_f32 v12, v12, v13
	v_cvt_pk_bf16_f32 v13, v14, v15
	v_cvt_pk_bf16_f32 v14, v8, v9
	v_cvt_pk_bf16_f32 v15, v10, v11
	global_store_dwordx4 v[192:193], v[12:15], off
	s_waitcnt vmcnt(9)
	v_lshlrev_b32_e32 v188, 16, v234
	v_and_b32_e32 v189, 0xffff0000, v234
	v_lshlrev_b32_e32 v190, 16, v235
	v_and_b32_e32 v191, 0xffff0000, v235
	v_lshlrev_b32_e32 v246, 16, v236
	v_and_b32_e32 v247, 0xffff0000, v236
	v_lshlrev_b32_e32 v248, 16, v237
	v_and_b32_e32 v249, 0xffff0000, v237
	v_pk_fma_f32 v[4:5], v[4:5], v[76:77], v[188:189]
	v_pk_fma_f32 v[6:7], v[6:7], v[78:79], v[190:191]
	v_pk_fma_f32 v[0:1], v[0:1], v[72:73], v[246:247]
	v_pk_fma_f32 v[2:3], v[2:3], v[74:75], v[248:249]
	v_cvt_pk_bf16_f32 v4, v4, v5
	v_cvt_pk_bf16_f32 v5, v6, v7
	v_cvt_pk_bf16_f32 v6, v0, v1
	v_cvt_pk_bf16_f32 v7, v2, v3
	global_store_dwordx4 v[192:193], v[4:7], off offset:256
	s_branch .Lwo_epi_done

.LBB0_773:
	s_add_u32 s22, s20, 0xfff80080
	s_addc_u32 s23, s21, -1
	s_add_i32 s61, 0, 0x10000
	ds_read_b128 v[144:147], v230
	ds_read_b128 v[148:151], v230 offset:1024
	ds_read_b128 v[162:165], v230 offset:2048
	ds_read_b128 v[166:169], v230 offset:3072
	s_cmp_eq_u32 s60, 28
	s_cselect_b32 s47, s35, s23
	s_cselect_b32 s46, s56, s22
	s_cselect_b32 s23, s25, s59
	s_cselect_b32 s22, s57, s58
	s_add_i32 m0, s5, 0xc000
	ds_read_b128 v[170:173], v143
	ds_read_b128 v[174:177], v143 offset:1024
	ds_read_b128 v[178:181], v143 offset:2048
	ds_read_b128 v[182:185], v143 offset:3072
	ds_read_b128 v[186:189], v143 offset:4096
	ds_read_b128 v[190:193], v143 offset:5120
	ds_read_b128 v[206:209], v143 offset:6144
	ds_read_b128 v[210:213], v143 offset:7168
	global_load_lds_dwordx4 v134, s[20:21]
	s_add_i32 m0, s5, 0xe000
	s_nop 0
	global_load_lds_dwordx4 v136, s[20:21]
	s_waitcnt lgkmcnt(8)
	s_barrier
	s_waitcnt lgkmcnt(0)
	v_mfma_f32_16x16x32_bf16 v[124:127], v[144:147], v[170:173], v[124:127]
	v_mfma_f32_16x16x32_bf16 v[120:123], v[162:165], v[170:173], v[120:123]
	v_mfma_f32_16x16x32_bf16 v[108:111], v[144:147], v[178:181], v[108:111]
	v_mfma_f32_16x16x32_bf16 v[104:107], v[162:165], v[178:181], v[104:107]
	v_mfma_f32_16x16x32_bf16 v[92:95], v[144:147], v[186:189], v[92:95]
	v_mfma_f32_16x16x32_bf16 v[88:91], v[162:165], v[186:189], v[88:91]
	v_mfma_f32_16x16x32_bf16 v[76:79], v[144:147], v[206:209], v[76:79]
	v_mfma_f32_16x16x32_bf16 v[72:75], v[162:165], v[206:209], v[72:75]
	v_mfma_f32_16x16x32_bf16 v[124:127], v[148:151], v[174:177], v[124:127]
	v_mfma_f32_16x16x32_bf16 v[120:123], v[166:169], v[174:177], v[120:123]
	v_mfma_f32_16x16x32_bf16 v[108:111], v[148:151], v[182:185], v[108:111]
	v_mfma_f32_16x16x32_bf16 v[104:107], v[166:169], v[182:185], v[104:107]
	v_mfma_f32_16x16x32_bf16 v[92:95], v[148:151], v[190:193], v[92:95]
	v_mfma_f32_16x16x32_bf16 v[88:91], v[166:169], v[190:193], v[88:91]
	v_mfma_f32_16x16x32_bf16 v[76:79], v[148:151], v[210:213], v[76:79]
	v_mfma_f32_16x16x32_bf16 v[72:75], v[166:169], v[210:213], v[72:75]
	s_barrier
	s_add_i32 s68, 0, 0x14000
	s_add_i32 s61, s61, s4
	ds_read_b128 v[214:217], v231
	ds_read_b128 v[218:221], v231 offset:1024
	ds_read_b128 v[222:225], v231 offset:2048
	ds_read_b128 v[226:229], v231 offset:3072
	s_mov_b32 m0, s61
	s_nop 0
	global_load_lds_dwordx4 v152, s[22:23]
	s_add_i32 m0, s61, 0x2000
	s_nop 0
	global_load_lds_dwordx4 v132, s[22:23]
	s_barrier
	s_waitcnt lgkmcnt(0)
	v_mfma_f32_16x16x32_bf16 v[116:119], v[214:217], v[170:173], v[116:119]
	v_mfma_f32_16x16x32_bf16 v[112:115], v[222:225], v[170:173], v[112:115]
	v_mfma_f32_16x16x32_bf16 v[100:103], v[214:217], v[178:181], v[100:103]
	v_mfma_f32_16x16x32_bf16 v[96:99], v[222:225], v[178:181], v[96:99]
	v_mfma_f32_16x16x32_bf16 v[84:87], v[214:217], v[186:189], v[84:87]
	v_mfma_f32_16x16x32_bf16 v[80:83], v[222:225], v[186:189], v[80:83]
	v_mfma_f32_16x16x32_bf16 v[68:71], v[214:217], v[206:209], v[68:71]
	v_mfma_f32_16x16x32_bf16 v[64:67], v[222:225], v[206:209], v[64:67]
	v_mfma_f32_16x16x32_bf16 v[116:119], v[218:221], v[174:177], v[116:119]
	v_mfma_f32_16x16x32_bf16 v[112:115], v[226:229], v[174:177], v[112:115]
	v_mfma_f32_16x16x32_bf16 v[100:103], v[218:221], v[182:185], v[100:103]
	v_mfma_f32_16x16x32_bf16 v[96:99], v[226:229], v[182:185], v[96:99]
	v_mfma_f32_16x16x32_bf16 v[84:87], v[218:221], v[190:193], v[84:87]
	v_mfma_f32_16x16x32_bf16 v[80:83], v[226:229], v[190:193], v[80:83]
	v_mfma_f32_16x16x32_bf16 v[68:71], v[218:221], v[210:213], v[68:71]
	v_mfma_f32_16x16x32_bf16 v[64:67], v[226:229], v[210:213], v[64:67]
	s_barrier
	s_mov_b32 m0, s5
	s_add_u32 s98, s46, 0x80
	s_addc_u32 s99, s47, 0
	ds_read_b128 v[170:173], v143 offset:16384
	ds_read_b128 v[174:177], v143 offset:17408
	ds_read_b128 v[178:181], v143 offset:18432
	ds_read_b128 v[182:185], v143 offset:19456
	ds_read_b128 v[186:189], v143 offset:20480
	ds_read_b128 v[190:193], v143 offset:21504
	ds_read_b128 v[206:209], v143 offset:22528
	ds_read_b128 v[210:213], v143 offset:23552
	global_load_lds_dwordx4 v128, s[46:47]
	s_mov_b32 m0, s50
	s_nop 0
	global_load_lds_dwordx4 v130, s[46:47]
	s_barrier
	s_waitcnt lgkmcnt(0)
	v_mfma_f32_16x16x32_bf16 v[60:63], v[144:147], v[170:173], v[60:63]
	v_mfma_f32_16x16x32_bf16 v[56:59], v[162:165], v[170:173], v[56:59]
	v_mfma_f32_16x16x32_bf16 v[44:47], v[144:147], v[178:181], v[44:47]
	v_mfma_f32_16x16x32_bf16 v[40:43], v[162:165], v[178:181], v[40:43]
	v_mfma_f32_16x16x32_bf16 v[28:31], v[144:147], v[186:189], v[28:31]
	v_mfma_f32_16x16x32_bf16 v[24:27], v[162:165], v[186:189], v[24:27]
	v_mfma_f32_16x16x32_bf16 v[12:15], v[144:147], v[206:209], v[12:15]
	v_mfma_f32_16x16x32_bf16 v[8:11], v[162:165], v[206:209], v[8:11]
	v_mfma_f32_16x16x32_bf16 v[60:63], v[148:151], v[174:177], v[60:63]
	v_mfma_f32_16x16x32_bf16 v[56:59], v[166:169], v[174:177], v[56:59]
	v_mfma_f32_16x16x32_bf16 v[44:47], v[148:151], v[182:185], v[44:47]
	v_mfma_f32_16x16x32_bf16 v[40:43], v[166:169], v[182:185], v[40:43]
	v_mfma_f32_16x16x32_bf16 v[28:31], v[148:151], v[190:193], v[28:31]
	v_mfma_f32_16x16x32_bf16 v[24:27], v[166:169], v[190:193], v[24:27]
	v_mfma_f32_16x16x32_bf16 v[12:15], v[148:151], v[210:213], v[12:15]
	v_mfma_f32_16x16x32_bf16 v[8:11], v[166:169], v[210:213], v[8:11]
	s_barrier
	s_add_u32 s62, s22, 0x80000
	s_addc_u32 s63, s23, 0
	s_add_i32 s61, s68, s4
	s_mov_b32 m0, s61
	s_nop 0
	global_load_lds_dwordx4 v152, s[62:63]
	s_add_i32 m0, s61, 0x2000
	s_nop 0
	global_load_lds_dwordx4 v132, s[62:63]
	s_waitcnt vmcnt(6)
	s_barrier
	v_mfma_f32_16x16x32_bf16 v[52:55], v[214:217], v[170:173], v[52:55]
	v_mfma_f32_16x16x32_bf16 v[48:51], v[222:225], v[170:173], v[48:51]
	v_mfma_f32_16x16x32_bf16 v[36:39], v[214:217], v[178:181], v[36:39]
	v_mfma_f32_16x16x32_bf16 v[32:35], v[222:225], v[178:181], v[32:35]
	v_mfma_f32_16x16x32_bf16 v[20:23], v[214:217], v[186:189], v[20:23]
	v_mfma_f32_16x16x32_bf16 v[16:19], v[222:225], v[186:189], v[16:19]
	v_mfma_f32_16x16x32_bf16 v[4:7], v[214:217], v[206:209], v[4:7]
	v_mfma_f32_16x16x32_bf16 v[0:3], v[222:225], v[206:209], v[0:3]
	v_mfma_f32_16x16x32_bf16 v[52:55], v[218:221], v[174:177], v[52:55]
	v_mfma_f32_16x16x32_bf16 v[48:51], v[226:229], v[174:177], v[48:51]
	v_mfma_f32_16x16x32_bf16 v[36:39], v[218:221], v[182:185], v[36:39]
	v_mfma_f32_16x16x32_bf16 v[32:35], v[226:229], v[182:185], v[32:35]
	v_mfma_f32_16x16x32_bf16 v[20:23], v[218:221], v[190:193], v[20:23]
	v_mfma_f32_16x16x32_bf16 v[16:19], v[226:229], v[190:193], v[16:19]
	v_mfma_f32_16x16x32_bf16 v[4:7], v[218:221], v[210:213], v[4:7]
	v_mfma_f32_16x16x32_bf16 v[0:3], v[226:229], v[210:213], v[0:3]
	s_barrier
	s_add_i32 s61, 0, 0x18000
	ds_read_b128 v[144:147], v232
	ds_read_b128 v[148:151], v232 offset:1024
	ds_read_b128 v[162:165], v232 offset:2048
	ds_read_b128 v[166:169], v232 offset:3072
	s_add_u32 s46, s46, 0x80000
	s_addc_u32 s47, s47, 0
	s_mov_b32 m0, s51
	ds_read_b128 v[170:173], v143 offset:32768
	ds_read_b128 v[174:177], v143 offset:33792
	ds_read_b128 v[178:181], v143 offset:34816
	ds_read_b128 v[182:185], v143 offset:35840
	ds_read_b128 v[186:189], v143 offset:36864
	ds_read_b128 v[190:193], v143 offset:37888
	ds_read_b128 v[206:209], v143 offset:38912
	ds_read_b128 v[210:213], v143 offset:39936
	global_load_lds_dwordx4 v128, s[46:47]
	s_mov_b32 m0, s52
	s_nop 0
	global_load_lds_dwordx4 v130, s[46:47]
	s_waitcnt lgkmcnt(8)
	s_barrier
	s_waitcnt lgkmcnt(0)
	v_mfma_f32_16x16x32_bf16 v[124:127], v[144:147], v[170:173], v[124:127]
	v_mfma_f32_16x16x32_bf16 v[120:123], v[162:165], v[170:173], v[120:123]
	v_mfma_f32_16x16x32_bf16 v[108:111], v[144:147], v[178:181], v[108:111]
	v_mfma_f32_16x16x32_bf16 v[104:107], v[162:165], v[178:181], v[104:107]
	v_mfma_f32_16x16x32_bf16 v[92:95], v[144:147], v[186:189], v[92:95]
	v_mfma_f32_16x16x32_bf16 v[88:91], v[162:165], v[186:189], v[88:91]
	v_mfma_f32_16x16x32_bf16 v[76:79], v[144:147], v[206:209], v[76:79]
	v_mfma_f32_16x16x32_bf16 v[72:75], v[162:165], v[206:209], v[72:75]
	v_mfma_f32_16x16x32_bf16 v[124:127], v[148:151], v[174:177], v[124:127]
	v_mfma_f32_16x16x32_bf16 v[120:123], v[166:169], v[174:177], v[120:123]
	v_mfma_f32_16x16x32_bf16 v[108:111], v[148:151], v[182:185], v[108:111]
	v_mfma_f32_16x16x32_bf16 v[104:107], v[166:169], v[182:185], v[104:107]
	v_mfma_f32_16x16x32_bf16 v[92:95], v[148:151], v[190:193], v[92:95]
	v_mfma_f32_16x16x32_bf16 v[88:91], v[166:169], v[190:193], v[88:91]
	v_mfma_f32_16x16x32_bf16 v[76:79], v[148:151], v[210:213], v[76:79]
	v_mfma_f32_16x16x32_bf16 v[72:75], v[166:169], v[210:213], v[72:75]
	s_barrier
	s_add_i32 s46, 0, 0x1c000
	s_add_i32 s47, s61, s4
	s_add_u32 s100, s22, 0x80
	s_addc_u32 s101, s23, 0
	s_mov_b32 m0, s47
	ds_read_b128 v[214:217], v233
	ds_read_b128 v[218:221], v233 offset:1024
	ds_read_b128 v[222:225], v233 offset:2048
	ds_read_b128 v[226:229], v233 offset:3072
	global_load_lds_dwordx4 v152, s[100:101]
	s_add_i32 m0, s47, 0x2000
	s_nop 0
	global_load_lds_dwordx4 v132, s[100:101]
	s_barrier
	s_waitcnt lgkmcnt(0)
	v_mfma_f32_16x16x32_bf16 v[116:119], v[214:217], v[170:173], v[116:119]
	v_mfma_f32_16x16x32_bf16 v[112:115], v[222:225], v[170:173], v[112:115]
	v_mfma_f32_16x16x32_bf16 v[100:103], v[214:217], v[178:181], v[100:103]
	v_mfma_f32_16x16x32_bf16 v[96:99], v[222:225], v[178:181], v[96:99]
	v_mfma_f32_16x16x32_bf16 v[84:87], v[214:217], v[186:189], v[84:87]
	v_mfma_f32_16x16x32_bf16 v[80:83], v[222:225], v[186:189], v[80:83]
	v_mfma_f32_16x16x32_bf16 v[68:71], v[214:217], v[206:209], v[68:71]
	v_mfma_f32_16x16x32_bf16 v[64:67], v[222:225], v[206:209], v[64:67]
	v_mfma_f32_16x16x32_bf16 v[116:119], v[218:221], v[174:177], v[116:119]
	v_mfma_f32_16x16x32_bf16 v[112:115], v[226:229], v[174:177], v[112:115]
	v_mfma_f32_16x16x32_bf16 v[100:103], v[218:221], v[182:185], v[100:103]
	v_mfma_f32_16x16x32_bf16 v[96:99], v[226:229], v[182:185], v[96:99]
	v_mfma_f32_16x16x32_bf16 v[84:87], v[218:221], v[190:193], v[84:87]
	v_mfma_f32_16x16x32_bf16 v[80:83], v[226:229], v[190:193], v[80:83]
	v_mfma_f32_16x16x32_bf16 v[68:71], v[218:221], v[210:213], v[68:71]
	v_mfma_f32_16x16x32_bf16 v[64:67], v[226:229], v[210:213], v[64:67]
	s_barrier
	s_mov_b32 m0, s53
	ds_read_b128 v[170:173], v143 offset:49152
	ds_read_b128 v[174:177], v143 offset:50176
	ds_read_b128 v[178:181], v143 offset:51200
	ds_read_b128 v[182:185], v143 offset:52224
	ds_read_b128 v[186:189], v143 offset:53248
	ds_read_b128 v[190:193], v143 offset:54272
	ds_read_b128 v[206:209], v143 offset:55296
	ds_read_b128 v[210:213], v143 offset:56320
	global_load_lds_dwordx4 v128, s[98:99]
	s_mov_b32 m0, s54
	s_nop 0
	global_load_lds_dwordx4 v130, s[98:99]
	s_barrier
	s_waitcnt lgkmcnt(0)
	v_mfma_f32_16x16x32_bf16 v[60:63], v[144:147], v[170:173], v[60:63]
	v_mfma_f32_16x16x32_bf16 v[56:59], v[162:165], v[170:173], v[56:59]
	v_mfma_f32_16x16x32_bf16 v[44:47], v[144:147], v[178:181], v[44:47]
	v_mfma_f32_16x16x32_bf16 v[40:43], v[162:165], v[178:181], v[40:43]
	v_mfma_f32_16x16x32_bf16 v[28:31], v[144:147], v[186:189], v[28:31]
	v_mfma_f32_16x16x32_bf16 v[24:27], v[162:165], v[186:189], v[24:27]
	v_mfma_f32_16x16x32_bf16 v[12:15], v[144:147], v[206:209], v[12:15]
	v_mfma_f32_16x16x32_bf16 v[8:11], v[162:165], v[206:209], v[8:11]
	v_mfma_f32_16x16x32_bf16 v[60:63], v[148:151], v[174:177], v[60:63]
	v_mfma_f32_16x16x32_bf16 v[56:59], v[166:169], v[174:177], v[56:59]
	v_mfma_f32_16x16x32_bf16 v[44:47], v[148:151], v[182:185], v[44:47]
	v_mfma_f32_16x16x32_bf16 v[40:43], v[166:169], v[182:185], v[40:43]
	v_mfma_f32_16x16x32_bf16 v[28:31], v[148:151], v[190:193], v[28:31]
	v_mfma_f32_16x16x32_bf16 v[24:27], v[166:169], v[190:193], v[24:27]
	v_mfma_f32_16x16x32_bf16 v[12:15], v[148:151], v[210:213], v[12:15]
	v_mfma_f32_16x16x32_bf16 v[8:11], v[166:169], v[210:213], v[8:11]
	s_barrier
	s_add_u32 s22, s22, 0x80080
	s_addc_u32 s23, s23, 0
	s_add_i32 s46, s46, s4
	s_mov_b32 m0, s46
	s_nop 0
	global_load_lds_dwordx4 v152, s[22:23]
	s_add_i32 m0, s46, 0x2000
	s_nop 0
	global_load_lds_dwordx4 v132, s[22:23]
	s_add_i32 s60, s60, 2
	s_add_u32 s20, s20, 0x100
	s_addc_u32 s21, s21, 0
	s_add_u32 s58, s58, 0x100
	s_addc_u32 s59, s59, 0
	s_cmp_gt_u32 s60, 29
	s_waitcnt vmcnt(6)
	s_barrier
	v_mfma_f32_16x16x32_bf16 v[52:55], v[214:217], v[170:173], v[52:55]
	v_mfma_f32_16x16x32_bf16 v[48:51], v[222:225], v[170:173], v[48:51]
	v_mfma_f32_16x16x32_bf16 v[36:39], v[214:217], v[178:181], v[36:39]
	v_mfma_f32_16x16x32_bf16 v[32:35], v[222:225], v[178:181], v[32:35]
	v_mfma_f32_16x16x32_bf16 v[20:23], v[214:217], v[186:189], v[20:23]
	v_mfma_f32_16x16x32_bf16 v[16:19], v[222:225], v[186:189], v[16:19]
	v_mfma_f32_16x16x32_bf16 v[4:7], v[214:217], v[206:209], v[4:7]
	v_mfma_f32_16x16x32_bf16 v[0:3], v[222:225], v[206:209], v[0:3]
	v_mfma_f32_16x16x32_bf16 v[52:55], v[218:221], v[174:177], v[52:55]
	v_mfma_f32_16x16x32_bf16 v[48:51], v[226:229], v[174:177], v[48:51]
	v_mfma_f32_16x16x32_bf16 v[36:39], v[218:221], v[182:185], v[36:39]
	v_mfma_f32_16x16x32_bf16 v[32:35], v[226:229], v[182:185], v[32:35]
	v_mfma_f32_16x16x32_bf16 v[20:23], v[218:221], v[190:193], v[20:23]
	v_mfma_f32_16x16x32_bf16 v[16:19], v[226:229], v[190:193], v[16:19]
	v_mfma_f32_16x16x32_bf16 v[4:7], v[218:221], v[210:213], v[4:7]
	v_mfma_f32_16x16x32_bf16 v[0:3], v[226:229], v[210:213], v[0:3]
	s_barrier
	s_cbranch_scc0 .LBB0_773
	v_lshl_add_u32 v144, s7, 8, v140
	v_max_f32_e32 v120, v120, v120
	v_ashrrev_i32_e32 v145, 31, v144
	v_max_f32_e32 v120, 0, v120
	v_max_f32_e32 v121, v121, v121
	v_max_f32_e32 v122, v122, v122
	v_lshl_or_b32 v138, s6, 8, v142
	v_lshlrev_b64 v[146:147], 14, v[144:145]
	v_mul_f32_e32 v145, v120, v120
	v_max_f32_e32 v120, v125, v125
	v_max_f32_e32 v121, 0, v121
	v_max_f32_e32 v122, 0, v122
	v_ashrrev_i32_e32 v139, 31, v138
	v_max_f32_e32 v124, v124, v124
	v_max_f32_e32 v120, 0, v120
	v_mul_f32_e32 v125, v121, v121
	v_max_f32_e32 v121, v126, v126
	v_mul_f32_e32 v126, v122, v122
	v_max_f32_e32 v122, v127, v127
	v_max_f32_e32 v123, v123, v123
	v_lshl_add_u64 v[146:147], s[16:17], 0, v[146:147]
	v_lshlrev_b64 v[148:149], 1, v[138:139]
	v_max_f32_e32 v124, 0, v124
	v_mul_f32_e32 v120, v120, v120
	v_max_f32_e32 v121, 0, v121
	v_max_f32_e32 v122, 0, v122
	v_max_f32_e32 v123, 0, v123
	v_max_f32_e32 v112, v112, v112
	v_lshl_add_u64 v[138:139], v[146:147], 0, v[148:149]
	v_mul_f32_e32 v124, v124, v124
	v_mul_f32_e32 v121, v121, v121
	v_mul_f32_e32 v122, v122, v122
	v_mul_f32_e32 v123, v123, v123
	v_cvt_pk_bf16_f32 v120, v124, v120
	v_max_f32_e32 v112, 0, v112
	v_max_f32_e32 v113, v113, v113
	v_max_f32_e32 v114, v114, v114
	v_cvt_pk_bf16_f32 v121, v121, v122
	v_cvt_pk_bf16_f32 v122, v145, v125
	v_cvt_pk_bf16_f32 v123, v126, v123
	global_store_dwordx4 v[138:139], v[120:123], off
	v_max_f32_e32 v113, 0, v113
	v_max_f32_e32 v114, 0, v114
	v_mul_f32_e32 v120, v112, v112
	v_max_f32_e32 v112, v117, v117
	v_max_f32_e32 v116, v116, v116
	v_max_f32_e32 v112, 0, v112
	v_mul_f32_e32 v117, v113, v113
	v_max_f32_e32 v113, v118, v118
	v_mul_f32_e32 v118, v114, v114
	v_max_f32_e32 v114, v119, v119
	v_max_f32_e32 v115, v115, v115
	v_max_f32_e32 v116, 0, v116
	v_mul_f32_e32 v112, v112, v112
	v_max_f32_e32 v113, 0, v113
	v_max_f32_e32 v114, 0, v114
	v_max_f32_e32 v115, 0, v115
	v_mul_f32_e32 v116, v116, v116
	v_mul_f32_e32 v113, v113, v113
	v_mul_f32_e32 v114, v114, v114
	v_mul_f32_e32 v115, v115, v115
	v_cvt_pk_bf16_f32 v112, v116, v112
	v_max_f32_e32 v104, v104, v104
	v_cvt_pk_bf16_f32 v113, v113, v114
	v_cvt_pk_bf16_f32 v114, v120, v117
	v_cvt_pk_bf16_f32 v115, v118, v115
	global_store_dwordx4 v[138:139], v[112:115], off offset:256
	v_max_f32_e32 v104, 0, v104
	v_max_f32_e32 v105, v105, v105
	v_or_b32_e32 v112, 16, v144
	v_max_f32_e32 v106, v106, v106
	v_ashrrev_i32_e32 v113, 31, v112
	v_mul_f32_e32 v114, v104, v104
	v_max_f32_e32 v104, v109, v109
	v_max_f32_e32 v105, 0, v105
	v_max_f32_e32 v106, 0, v106
	v_lshlrev_b64 v[112:113], 14, v[112:113]
	v_max_f32_e32 v108, v108, v108
	v_max_f32_e32 v104, 0, v104
	v_mul_f32_e32 v109, v105, v105
	v_max_f32_e32 v105, v110, v110
	v_mul_f32_e32 v110, v106, v106
	v_max_f32_e32 v106, v111, v111
	v_max_f32_e32 v107, v107, v107
	v_lshl_add_u64 v[112:113], s[16:17], 0, v[112:113]
	v_max_f32_e32 v108, 0, v108
	v_mul_f32_e32 v104, v104, v104
	v_max_f32_e32 v105, 0, v105
	v_max_f32_e32 v106, 0, v106
	v_max_f32_e32 v107, 0, v107
	v_max_f32_e32 v96, v96, v96
	v_lshl_add_u64 v[112:113], v[112:113], 0, v[148:149]
	v_mul_f32_e32 v108, v108, v108
	v_mul_f32_e32 v105, v105, v105
	v_mul_f32_e32 v106, v106, v106
	v_mul_f32_e32 v107, v107, v107
	v_cvt_pk_bf16_f32 v104, v108, v104
	v_max_f32_e32 v96, 0, v96
	v_max_f32_e32 v97, v97, v97
	v_max_f32_e32 v98, v98, v98
	v_cvt_pk_bf16_f32 v105, v105, v106
	v_cvt_pk_bf16_f32 v106, v114, v109
	v_cvt_pk_bf16_f32 v107, v110, v107
	global_store_dwordx4 v[112:113], v[104:107], off
	v_max_f32_e32 v97, 0, v97
	v_max_f32_e32 v98, 0, v98
	v_mul_f32_e32 v104, v96, v96
	v_max_f32_e32 v96, v101, v101
	v_max_f32_e32 v100, v100, v100
	v_max_f32_e32 v96, 0, v96
	v_mul_f32_e32 v101, v97, v97
	v_max_f32_e32 v97, v102, v102
	v_mul_f32_e32 v102, v98, v98
	v_max_f32_e32 v98, v103, v103
	v_max_f32_e32 v99, v99, v99
	v_max_f32_e32 v100, 0, v100
	v_mul_f32_e32 v96, v96, v96
	v_max_f32_e32 v97, 0, v97
	v_max_f32_e32 v98, 0, v98
	v_max_f32_e32 v99, 0, v99
	v_mul_f32_e32 v100, v100, v100
	v_mul_f32_e32 v97, v97, v97
	v_mul_f32_e32 v98, v98, v98
	v_mul_f32_e32 v99, v99, v99
	v_cvt_pk_bf16_f32 v96, v100, v96
	v_max_f32_e32 v88, v88, v88
	v_cvt_pk_bf16_f32 v97, v97, v98
	v_cvt_pk_bf16_f32 v98, v104, v101
	v_cvt_pk_bf16_f32 v99, v102, v99
	global_store_dwordx4 v[112:113], v[96:99], off offset:256
	v_max_f32_e32 v88, 0, v88
	v_max_f32_e32 v89, v89, v89
	v_or_b32_e32 v96, 32, v144
	v_max_f32_e32 v90, v90, v90
	v_ashrrev_i32_e32 v97, 31, v96
	v_mul_f32_e32 v98, v88, v88
	v_max_f32_e32 v88, v93, v93
	v_max_f32_e32 v89, 0, v89
	v_max_f32_e32 v90, 0, v90
	v_lshlrev_b64 v[96:97], 14, v[96:97]
	v_max_f32_e32 v92, v92, v92
	v_max_f32_e32 v88, 0, v88
	v_mul_f32_e32 v93, v89, v89
	v_max_f32_e32 v89, v94, v94
	v_mul_f32_e32 v94, v90, v90
	v_max_f32_e32 v90, v95, v95
	v_max_f32_e32 v91, v91, v91
	v_lshl_add_u64 v[96:97], s[16:17], 0, v[96:97]
	v_max_f32_e32 v92, 0, v92
	v_mul_f32_e32 v88, v88, v88
	v_max_f32_e32 v89, 0, v89
	v_max_f32_e32 v90, 0, v90
	v_max_f32_e32 v91, 0, v91
	v_max_f32_e32 v80, v80, v80
	v_lshl_add_u64 v[96:97], v[96:97], 0, v[148:149]
	v_mul_f32_e32 v92, v92, v92
	v_mul_f32_e32 v89, v89, v89
	v_mul_f32_e32 v90, v90, v90
	v_mul_f32_e32 v91, v91, v91
	v_cvt_pk_bf16_f32 v88, v92, v88
	v_max_f32_e32 v80, 0, v80
	v_max_f32_e32 v81, v81, v81
	v_max_f32_e32 v82, v82, v82
	v_cvt_pk_bf16_f32 v89, v89, v90
	v_cvt_pk_bf16_f32 v90, v98, v93
	v_cvt_pk_bf16_f32 v91, v94, v91
	global_store_dwordx4 v[96:97], v[88:91], off
	v_max_f32_e32 v81, 0, v81
	v_max_f32_e32 v82, 0, v82
	v_mul_f32_e32 v88, v80, v80
	v_max_f32_e32 v80, v85, v85
	v_max_f32_e32 v84, v84, v84
	v_max_f32_e32 v80, 0, v80
	v_mul_f32_e32 v85, v81, v81
	v_max_f32_e32 v81, v86, v86
	v_mul_f32_e32 v86, v82, v82
	v_max_f32_e32 v82, v87, v87
	v_max_f32_e32 v83, v83, v83
	v_max_f32_e32 v84, 0, v84
	v_mul_f32_e32 v80, v80, v80
	v_max_f32_e32 v81, 0, v81
	v_max_f32_e32 v82, 0, v82
	v_max_f32_e32 v83, 0, v83
	v_mul_f32_e32 v84, v84, v84
	v_mul_f32_e32 v81, v81, v81
	v_mul_f32_e32 v82, v82, v82
	v_mul_f32_e32 v83, v83, v83
	v_cvt_pk_bf16_f32 v80, v84, v80
	v_max_f32_e32 v72, v72, v72
	v_cvt_pk_bf16_f32 v81, v81, v82
	v_cvt_pk_bf16_f32 v82, v88, v85
	v_cvt_pk_bf16_f32 v83, v86, v83
	global_store_dwordx4 v[96:97], v[80:83], off offset:256
	v_max_f32_e32 v72, 0, v72
	v_max_f32_e32 v73, v73, v73
	v_or_b32_e32 v80, 48, v144
	v_max_f32_e32 v74, v74, v74
	v_ashrrev_i32_e32 v81, 31, v80
	v_mul_f32_e32 v82, v72, v72
	v_max_f32_e32 v72, v77, v77
	v_max_f32_e32 v73, 0, v73
	v_max_f32_e32 v74, 0, v74
	v_lshlrev_b64 v[80:81], 14, v[80:81]
	v_max_f32_e32 v76, v76, v76
	v_max_f32_e32 v72, 0, v72
	v_mul_f32_e32 v77, v73, v73
	v_max_f32_e32 v73, v78, v78
	v_mul_f32_e32 v78, v74, v74
	v_max_f32_e32 v74, v79, v79
	v_max_f32_e32 v75, v75, v75
	v_lshl_add_u64 v[80:81], s[16:17], 0, v[80:81]
	v_max_f32_e32 v76, 0, v76
	v_mul_f32_e32 v72, v72, v72
	v_max_f32_e32 v73, 0, v73
	v_max_f32_e32 v74, 0, v74
	v_max_f32_e32 v75, 0, v75
	v_max_f32_e32 v64, v64, v64
	v_max_f32_e32 v65, v65, v65
	v_max_f32_e32 v66, v66, v66
	v_lshl_add_u64 v[80:81], v[80:81], 0, v[148:149]
	v_mul_f32_e32 v76, v76, v76
	v_mul_f32_e32 v73, v73, v73
	v_mul_f32_e32 v74, v74, v74
	v_mul_f32_e32 v75, v75, v75
	v_cvt_pk_bf16_f32 v72, v76, v72
	v_max_f32_e32 v64, 0, v64
	v_max_f32_e32 v65, 0, v65
	v_max_f32_e32 v66, 0, v66
	v_cvt_pk_bf16_f32 v73, v73, v74
	v_cvt_pk_bf16_f32 v74, v82, v77
	v_cvt_pk_bf16_f32 v75, v78, v75
	global_store_dwordx4 v[80:81], v[72:75], off
	v_max_f32_e32 v68, v68, v68
	v_max_f32_e32 v67, v67, v67
	v_mul_f32_e32 v72, v64, v64
	v_max_f32_e32 v64, v69, v69
	v_mul_f32_e32 v69, v65, v65
	v_max_f32_e32 v65, v70, v70
	v_mul_f32_e32 v70, v66, v66
	v_max_f32_e32 v66, v71, v71
	v_max_f32_e32 v64, 0, v64
	v_max_f32_e32 v65, 0, v65
	v_max_f32_e32 v66, 0, v66
	v_max_f32_e32 v68, 0, v68
	v_mul_f32_e32 v64, v64, v64
	v_mul_f32_e32 v65, v65, v65
	v_max_f32_e32 v67, 0, v67
	v_mul_f32_e32 v66, v66, v66
	v_max_f32_e32 v56, v56, v56
	v_mul_f32_e32 v68, v68, v68
	v_mul_f32_e32 v67, v67, v67
	v_cvt_pk_bf16_f32 v64, v68, v64
	v_cvt_pk_bf16_f32 v65, v65, v66
	v_cvt_pk_bf16_f32 v66, v72, v69
	v_max_f32_e32 v56, 0, v56
	v_max_f32_e32 v57, v57, v57
	v_max_f32_e32 v58, v58, v58
	v_cvt_pk_bf16_f32 v67, v70, v67
	global_store_dwordx4 v[80:81], v[64:67], off offset:256
	v_max_f32_e32 v60, v60, v60
	v_max_f32_e32 v57, 0, v57
	v_mul_f32_e32 v66, v56, v56
	v_max_f32_e32 v56, v61, v61
	v_max_f32_e32 v58, 0, v58
	s_mov_b64 s[6:7], 0x200000
	v_max_f32_e32 v60, 0, v60
	v_max_f32_e32 v56, 0, v56
	v_mul_f32_e32 v61, v57, v57
	v_max_f32_e32 v57, v62, v62
	v_mul_f32_e32 v62, v58, v58
	v_max_f32_e32 v58, v63, v63
	v_lshl_add_u64 v[64:65], v[138:139], 0, s[6:7]
	v_mul_f32_e32 v60, v60, v60
	v_mul_f32_e32 v56, v56, v56
	v_max_f32_e32 v57, 0, v57
	v_max_f32_e32 v58, 0, v58
	v_max_f32_e32 v59, v59, v59
	s_mov_b32 s6, 0x200000
	v_mul_f32_e32 v57, v57, v57
	v_max_f32_e32 v59, 0, v59
	v_mul_f32_e32 v58, v58, v58
	v_cvt_pk_bf16_f32 v56, v60, v56
	v_add_co_u32_e32 v60, vcc, s6, v138
	v_max_f32_e32 v48, v48, v48
	v_max_f32_e32 v49, v49, v49
	v_max_f32_e32 v50, v50, v50
	v_mul_f32_e32 v59, v59, v59
	v_cvt_pk_bf16_f32 v57, v57, v58
	v_cvt_pk_bf16_f32 v58, v66, v61
	v_addc_co_u32_e32 v61, vcc, 0, v139, vcc
	v_max_f32_e32 v48, 0, v48
	v_max_f32_e32 v49, 0, v49
	v_max_f32_e32 v50, 0, v50
	v_cvt_pk_bf16_f32 v59, v62, v59
	global_store_dwordx4 v[60:61], v[56:59], off
	v_max_f32_e32 v52, v52, v52
	v_max_f32_e32 v51, v51, v51
	v_mul_f32_e32 v56, v48, v48
	v_max_f32_e32 v48, v53, v53
	v_mul_f32_e32 v53, v49, v49
	v_max_f32_e32 v49, v54, v54
	v_mul_f32_e32 v54, v50, v50
	v_max_f32_e32 v50, v55, v55
	v_max_f32_e32 v48, 0, v48
	v_max_f32_e32 v49, 0, v49
	v_max_f32_e32 v50, 0, v50
	v_max_f32_e32 v52, 0, v52
	v_mul_f32_e32 v48, v48, v48
	v_mul_f32_e32 v49, v49, v49
	v_max_f32_e32 v51, 0, v51
	v_mul_f32_e32 v50, v50, v50
	v_max_f32_e32 v40, v40, v40
	v_mul_f32_e32 v52, v52, v52
	v_mul_f32_e32 v51, v51, v51
	v_cvt_pk_bf16_f32 v48, v52, v48
	v_cvt_pk_bf16_f32 v49, v49, v50
	v_cvt_pk_bf16_f32 v50, v56, v53
	v_max_f32_e32 v40, 0, v40
	v_max_f32_e32 v41, v41, v41
	v_max_f32_e32 v42, v42, v42
	v_cvt_pk_bf16_f32 v51, v54, v51
	global_store_dwordx4 v[64:65], v[48:51], off offset:256
	v_max_f32_e32 v44, v44, v44
	v_max_f32_e32 v41, 0, v41
	v_mul_f32_e32 v50, v40, v40
	v_max_f32_e32 v40, v45, v45
	v_max_f32_e32 v42, 0, v42
	s_mov_b64 s[6:7], 0x240000
	v_max_f32_e32 v44, 0, v44
	v_max_f32_e32 v40, 0, v40
	v_mul_f32_e32 v45, v41, v41
	v_max_f32_e32 v41, v46, v46
	v_mul_f32_e32 v46, v42, v42
	v_max_f32_e32 v42, v47, v47
	v_lshl_add_u64 v[48:49], v[138:139], 0, s[6:7]
	v_mul_f32_e32 v44, v44, v44
	v_mul_f32_e32 v40, v40, v40
	v_max_f32_e32 v41, 0, v41
	v_max_f32_e32 v42, 0, v42
	v_max_f32_e32 v43, v43, v43
	s_mov_b32 s6, 0x240000
	v_mul_f32_e32 v41, v41, v41
	v_max_f32_e32 v43, 0, v43
	v_mul_f32_e32 v42, v42, v42
	v_cvt_pk_bf16_f32 v40, v44, v40
	v_add_co_u32_e32 v44, vcc, s6, v138
	v_max_f32_e32 v32, v32, v32
	v_max_f32_e32 v33, v33, v33
	v_max_f32_e32 v34, v34, v34
	v_mul_f32_e32 v43, v43, v43
	v_cvt_pk_bf16_f32 v41, v41, v42
	v_cvt_pk_bf16_f32 v42, v50, v45
	v_addc_co_u32_e32 v45, vcc, 0, v139, vcc
	v_max_f32_e32 v32, 0, v32
	v_max_f32_e32 v33, 0, v33
	v_max_f32_e32 v34, 0, v34
	v_cvt_pk_bf16_f32 v43, v46, v43
	global_store_dwordx4 v[44:45], v[40:43], off
	v_max_f32_e32 v36, v36, v36
	v_max_f32_e32 v35, v35, v35
	v_mul_f32_e32 v40, v32, v32
	v_max_f32_e32 v32, v37, v37
	v_mul_f32_e32 v37, v33, v33
	v_max_f32_e32 v33, v38, v38
	v_mul_f32_e32 v38, v34, v34
	v_max_f32_e32 v34, v39, v39
	v_max_f32_e32 v32, 0, v32
	v_max_f32_e32 v33, 0, v33
	v_max_f32_e32 v34, 0, v34
	v_max_f32_e32 v36, 0, v36
	v_mul_f32_e32 v32, v32, v32
	v_mul_f32_e32 v33, v33, v33
	v_max_f32_e32 v35, 0, v35
	v_mul_f32_e32 v34, v34, v34
	v_max_f32_e32 v24, v24, v24
	v_mul_f32_e32 v36, v36, v36
	v_mul_f32_e32 v35, v35, v35
	v_cvt_pk_bf16_f32 v32, v36, v32
	v_cvt_pk_bf16_f32 v33, v33, v34
	v_cvt_pk_bf16_f32 v34, v40, v37
	v_max_f32_e32 v24, 0, v24
	v_max_f32_e32 v25, v25, v25
	v_max_f32_e32 v26, v26, v26
	v_cvt_pk_bf16_f32 v35, v38, v35
	global_store_dwordx4 v[48:49], v[32:35], off offset:256
	v_max_f32_e32 v28, v28, v28
	v_max_f32_e32 v25, 0, v25
	v_mul_f32_e32 v34, v24, v24
	v_max_f32_e32 v24, v29, v29
	v_max_f32_e32 v26, 0, v26
	s_mov_b64 s[6:7], 0x280000
	v_max_f32_e32 v28, 0, v28
	v_max_f32_e32 v24, 0, v24
	v_mul_f32_e32 v29, v25, v25
	v_max_f32_e32 v25, v30, v30
	v_mul_f32_e32 v30, v26, v26
	v_max_f32_e32 v26, v31, v31
	v_lshl_add_u64 v[32:33], v[138:139], 0, s[6:7]
	v_mul_f32_e32 v28, v28, v28
	v_mul_f32_e32 v24, v24, v24
	v_max_f32_e32 v25, 0, v25
	v_max_f32_e32 v26, 0, v26
	v_max_f32_e32 v27, v27, v27
	s_mov_b32 s6, 0x280000
	v_mul_f32_e32 v25, v25, v25
	v_max_f32_e32 v27, 0, v27
	v_mul_f32_e32 v26, v26, v26
	v_cvt_pk_bf16_f32 v24, v28, v24
	v_add_co_u32_e32 v28, vcc, s6, v138
	v_max_f32_e32 v16, v16, v16
	v_max_f32_e32 v17, v17, v17
	v_max_f32_e32 v18, v18, v18
	v_mul_f32_e32 v27, v27, v27
	v_cvt_pk_bf16_f32 v25, v25, v26
	v_cvt_pk_bf16_f32 v26, v34, v29
	v_addc_co_u32_e32 v29, vcc, 0, v139, vcc
	v_max_f32_e32 v16, 0, v16
	v_max_f32_e32 v17, 0, v17
	v_max_f32_e32 v18, 0, v18
	v_cvt_pk_bf16_f32 v27, v30, v27
	global_store_dwordx4 v[28:29], v[24:27], off
	v_max_f32_e32 v20, v20, v20
	v_max_f32_e32 v19, v19, v19
	v_mul_f32_e32 v24, v16, v16
	v_max_f32_e32 v16, v21, v21
	v_mul_f32_e32 v21, v17, v17
	v_max_f32_e32 v17, v22, v22
	v_mul_f32_e32 v22, v18, v18
	v_max_f32_e32 v18, v23, v23
	v_max_f32_e32 v16, 0, v16
	v_max_f32_e32 v17, 0, v17
	v_max_f32_e32 v18, 0, v18
	v_max_f32_e32 v20, 0, v20
	v_mul_f32_e32 v16, v16, v16
	v_mul_f32_e32 v17, v17, v17
	v_max_f32_e32 v19, 0, v19
	v_mul_f32_e32 v18, v18, v18
	v_max_f32_e32 v8, v8, v8
	v_mul_f32_e32 v20, v20, v20
	v_mul_f32_e32 v19, v19, v19
	v_cvt_pk_bf16_f32 v16, v20, v16
	v_cvt_pk_bf16_f32 v17, v17, v18
	v_cvt_pk_bf16_f32 v18, v24, v21
	v_max_f32_e32 v8, 0, v8
	v_max_f32_e32 v9, v9, v9
	v_max_f32_e32 v10, v10, v10
	v_cvt_pk_bf16_f32 v19, v22, v19
	global_store_dwordx4 v[32:33], v[16:19], off offset:256
	v_max_f32_e32 v12, v12, v12
	v_max_f32_e32 v9, 0, v9
	v_mul_f32_e32 v18, v8, v8
	v_max_f32_e32 v8, v13, v13
	v_max_f32_e32 v10, 0, v10
	s_mov_b64 s[6:7], 0x2c0000
	v_max_f32_e32 v12, 0, v12
	v_max_f32_e32 v8, 0, v8
	v_mul_f32_e32 v13, v9, v9
	v_max_f32_e32 v9, v14, v14
	v_mul_f32_e32 v14, v10, v10
	v_max_f32_e32 v10, v15, v15
	v_lshl_add_u64 v[16:17], v[138:139], 0, s[6:7]
	v_mul_f32_e32 v12, v12, v12
	v_mul_f32_e32 v8, v8, v8
	v_max_f32_e32 v9, 0, v9
	v_max_f32_e32 v10, 0, v10
	v_max_f32_e32 v11, v11, v11
	s_mov_b32 s6, 0x2c0000
	v_mul_f32_e32 v9, v9, v9
	v_max_f32_e32 v11, 0, v11
	v_mul_f32_e32 v10, v10, v10
	v_cvt_pk_bf16_f32 v8, v12, v8
	v_add_co_u32_e32 v12, vcc, s6, v138
	v_max_f32_e32 v0, v0, v0
	v_max_f32_e32 v1, v1, v1
	v_max_f32_e32 v2, v2, v2
	v_mul_f32_e32 v11, v11, v11
	v_cvt_pk_bf16_f32 v9, v9, v10
	v_cvt_pk_bf16_f32 v10, v18, v13
	v_addc_co_u32_e32 v13, vcc, 0, v139, vcc
	v_max_f32_e32 v0, 0, v0
	v_max_f32_e32 v1, 0, v1
	v_max_f32_e32 v2, 0, v2
	v_cvt_pk_bf16_f32 v11, v14, v11
	global_store_dwordx4 v[12:13], v[8:11], off
	v_max_f32_e32 v3, v3, v3
	v_max_f32_e32 v4, v4, v4
	v_mul_f32_e32 v8, v0, v0
	v_max_f32_e32 v0, v5, v5
	v_mul_f32_e32 v5, v1, v1
	v_max_f32_e32 v1, v6, v6
	v_mul_f32_e32 v6, v2, v2
	v_max_f32_e32 v2, v7, v7
	v_max_f32_e32 v0, 0, v0
	v_max_f32_e32 v1, 0, v1
	v_max_f32_e32 v2, 0, v2
	v_max_f32_e32 v3, 0, v3
	v_max_f32_e32 v4, 0, v4
	v_mul_f32_e32 v0, v0, v0
	v_mul_f32_e32 v1, v1, v1
	v_mul_f32_e32 v2, v2, v2
	v_mul_f32_e32 v3, v3, v3
	s_and_b64 vcc, exec, s[38:39]
	s_mov_b32 s6, s24
	s_mov_b32 s7, s34
	s_mov_b64 s[22:23], s[44:45]
	s_mov_b64 s[20:21], s[42:43]
	v_mul_f32_e32 v4, v4, v4
	v_cvt_pk_bf16_f32 v0, v4, v0
	v_cvt_pk_bf16_f32 v1, v1, v2
	v_cvt_pk_bf16_f32 v2, v8, v5
	v_cvt_pk_bf16_f32 v3, v6, v3
	global_store_dwordx4 v[16:17], v[0:3], off offset:256
	s_cbranch_vccz .LBB0_770
	s_waitcnt vmcnt(0)
	v_readlane_b32 s34, v253, 45
	s_cmpk_gt_u32 s14, 0xff
	v_readlane_b32 s35, v253, 46
	s_cbranch_scc1 .LBB0_777
	s_barrier

.LBB0_836:
	s_add_u32 s22, s20, 0xffe00080
	s_addc_u32 s23, s21, -1
	s_add_i32 s78, 0, 0x10000
	ds_read_b128 v[120:123], v248
	ds_read_b128 v[124:127], v248 offset:1024
	ds_read_b128 v[132:135], v248 offset:2048
	ds_read_b128 v[136:139], v248 offset:3072
	s_cmpk_eq_i32 s69, 0x7c
	s_cselect_b32 s35, s6, s23
	s_cselect_b32 s34, s7, s22
	s_cselect_b32 s23, s1, s68
	s_cselect_b32 s22, s17, s63
	s_add_i32 m0, s52, 0xc000
	ds_read_b128 v[186:189], v185
	ds_read_b128 v[190:193], v185 offset:1024
	ds_read_b128 v[206:209], v185 offset:2048
	ds_read_b128 v[210:213], v185 offset:3072
	ds_read_b128 v[214:217], v185 offset:4096
	ds_read_b128 v[218:221], v185 offset:5120
	ds_read_b128 v[222:225], v185 offset:6144
	ds_read_b128 v[226:229], v185 offset:7168
	global_load_lds_dwordx4 v176, s[20:21]
	s_add_i32 m0, s52, 0xe000
	s_nop 0
	global_load_lds_dwordx4 v178, s[20:21]
	s_waitcnt lgkmcnt(8)
	s_barrier
	s_waitcnt lgkmcnt(0)
	v_mfma_f32_16x16x32_bf16 v[140:143], v[120:123], v[186:189], v[140:143]
	v_mfma_f32_16x16x32_bf16 v[128:131], v[132:135], v[186:189], v[128:131]
	v_mfma_f32_16x16x32_bf16 v[112:115], v[120:123], v[206:209], v[112:115]
	v_mfma_f32_16x16x32_bf16 v[104:107], v[132:135], v[206:209], v[104:107]
	v_mfma_f32_16x16x32_bf16 v[96:99], v[120:123], v[214:217], v[96:99]
	v_mfma_f32_16x16x32_bf16 v[88:91], v[132:135], v[214:217], v[88:91]
	v_mfma_f32_16x16x32_bf16 v[80:83], v[120:123], v[222:225], v[80:83]
	v_mfma_f32_16x16x32_bf16 v[72:75], v[132:135], v[222:225], v[72:75]
	v_mfma_f32_16x16x32_bf16 v[140:143], v[124:127], v[190:193], v[140:143]
	v_mfma_f32_16x16x32_bf16 v[128:131], v[136:139], v[190:193], v[128:131]
	v_mfma_f32_16x16x32_bf16 v[112:115], v[124:127], v[210:213], v[112:115]
	v_mfma_f32_16x16x32_bf16 v[104:107], v[136:139], v[210:213], v[104:107]
	v_mfma_f32_16x16x32_bf16 v[96:99], v[124:127], v[218:221], v[96:99]
	v_mfma_f32_16x16x32_bf16 v[88:91], v[136:139], v[218:221], v[88:91]
	v_mfma_f32_16x16x32_bf16 v[80:83], v[124:127], v[226:229], v[80:83]
	v_mfma_f32_16x16x32_bf16 v[72:75], v[136:139], v[226:229], v[72:75]
	s_barrier
	s_add_i32 s80, 0, 0x14000
	s_add_i32 s78, s78, s51
	ds_read_b128 v[230:233], v249
	ds_read_b128 v[234:237], v249 offset:1024
	ds_read_b128 v[238:241], v249 offset:2048
	ds_read_b128 v[242:245], v249 offset:3072
	s_mov_b32 m0, s78
	s_nop 0
	global_load_lds_dwordx4 v152, s[22:23]
	s_add_i32 m0, s78, 0x2000
	s_nop 0
	global_load_lds_dwordx4 v144, s[22:23]
	s_barrier
	s_waitcnt lgkmcnt(0)
	v_mfma_f32_16x16x32_bf16 v[116:119], v[230:233], v[186:189], v[116:119]
	v_mfma_f32_16x16x32_bf16 v[108:111], v[238:241], v[186:189], v[108:111]
	v_mfma_f32_16x16x32_bf16 v[100:103], v[230:233], v[206:209], v[100:103]
	v_mfma_f32_16x16x32_bf16 v[92:95], v[238:241], v[206:209], v[92:95]
	v_mfma_f32_16x16x32_bf16 v[84:87], v[230:233], v[214:217], v[84:87]
	v_mfma_f32_16x16x32_bf16 v[76:79], v[238:241], v[214:217], v[76:79]
	v_mfma_f32_16x16x32_bf16 v[68:71], v[230:233], v[222:225], v[68:71]
	v_mfma_f32_16x16x32_bf16 v[64:67], v[238:241], v[222:225], v[64:67]
	v_mfma_f32_16x16x32_bf16 v[116:119], v[234:237], v[190:193], v[116:119]
	v_mfma_f32_16x16x32_bf16 v[108:111], v[242:245], v[190:193], v[108:111]
	v_mfma_f32_16x16x32_bf16 v[100:103], v[234:237], v[210:213], v[100:103]
	v_mfma_f32_16x16x32_bf16 v[92:95], v[242:245], v[210:213], v[92:95]
	v_mfma_f32_16x16x32_bf16 v[84:87], v[234:237], v[218:221], v[84:87]
	v_mfma_f32_16x16x32_bf16 v[76:79], v[242:245], v[218:221], v[76:79]
	v_mfma_f32_16x16x32_bf16 v[68:71], v[234:237], v[226:229], v[68:71]
	v_mfma_f32_16x16x32_bf16 v[64:67], v[242:245], v[226:229], v[64:67]
	s_barrier
	s_mov_b32 m0, s52
	s_add_u32 s98, s34, 0x80
	s_addc_u32 s99, s35, 0
	ds_read_b128 v[186:189], v185 offset:16384
	ds_read_b128 v[190:193], v185 offset:17408
	ds_read_b128 v[206:209], v185 offset:18432
	ds_read_b128 v[210:213], v185 offset:19456
	ds_read_b128 v[214:217], v185 offset:20480
	ds_read_b128 v[218:221], v185 offset:21504
	ds_read_b128 v[222:225], v185 offset:22528
	ds_read_b128 v[226:229], v185 offset:23552
	global_load_lds_dwordx4 v148, s[34:35]
	s_mov_b32 m0, s53
	s_nop 0
	global_load_lds_dwordx4 v146, s[34:35]
	s_barrier
	s_waitcnt lgkmcnt(0)
	v_mfma_f32_16x16x32_bf16 v[60:63], v[120:123], v[186:189], v[60:63]
	v_mfma_f32_16x16x32_bf16 v[56:59], v[132:135], v[186:189], v[56:59]
	v_mfma_f32_16x16x32_bf16 v[48:51], v[120:123], v[206:209], v[48:51]
	v_mfma_f32_16x16x32_bf16 v[40:43], v[132:135], v[206:209], v[40:43]
	v_mfma_f32_16x16x32_bf16 v[32:35], v[120:123], v[214:217], v[32:35]
	v_mfma_f32_16x16x32_bf16 v[24:27], v[132:135], v[214:217], v[24:27]
	v_mfma_f32_16x16x32_bf16 v[16:19], v[120:123], v[222:225], v[16:19]
	v_mfma_f32_16x16x32_bf16 v[8:11], v[132:135], v[222:225], v[8:11]
	v_mfma_f32_16x16x32_bf16 v[60:63], v[124:127], v[190:193], v[60:63]
	v_mfma_f32_16x16x32_bf16 v[56:59], v[136:139], v[190:193], v[56:59]
	v_mfma_f32_16x16x32_bf16 v[48:51], v[124:127], v[210:213], v[48:51]
	v_mfma_f32_16x16x32_bf16 v[40:43], v[136:139], v[210:213], v[40:43]
	v_mfma_f32_16x16x32_bf16 v[32:35], v[124:127], v[218:221], v[32:35]
	v_mfma_f32_16x16x32_bf16 v[24:27], v[136:139], v[218:221], v[24:27]
	v_mfma_f32_16x16x32_bf16 v[16:19], v[124:127], v[226:229], v[16:19]
	v_mfma_f32_16x16x32_bf16 v[8:11], v[136:139], v[226:229], v[8:11]
	s_barrier
	s_add_u32 s78, s22, 0x200000
	s_addc_u32 s79, s23, 0
	s_add_i32 s80, s80, s51
	s_mov_b32 m0, s80
	s_nop 0
	global_load_lds_dwordx4 v152, s[78:79]
	s_add_i32 m0, s80, 0x2000
	s_nop 0
	global_load_lds_dwordx4 v144, s[78:79]
	s_waitcnt vmcnt(6)
	s_barrier
	v_mfma_f32_16x16x32_bf16 v[52:55], v[230:233], v[186:189], v[52:55]
	v_mfma_f32_16x16x32_bf16 v[44:47], v[238:241], v[186:189], v[44:47]
	v_mfma_f32_16x16x32_bf16 v[36:39], v[230:233], v[206:209], v[36:39]
	v_mfma_f32_16x16x32_bf16 v[28:31], v[238:241], v[206:209], v[28:31]
	v_mfma_f32_16x16x32_bf16 v[20:23], v[230:233], v[214:217], v[20:23]
	v_mfma_f32_16x16x32_bf16 v[12:15], v[238:241], v[214:217], v[12:15]
	v_mfma_f32_16x16x32_bf16 v[4:7], v[230:233], v[222:225], v[4:7]
	v_mfma_f32_16x16x32_bf16 v[0:3], v[238:241], v[222:225], v[0:3]
	v_mfma_f32_16x16x32_bf16 v[52:55], v[234:237], v[190:193], v[52:55]
	v_mfma_f32_16x16x32_bf16 v[44:47], v[242:245], v[190:193], v[44:47]
	v_mfma_f32_16x16x32_bf16 v[36:39], v[234:237], v[210:213], v[36:39]
	v_mfma_f32_16x16x32_bf16 v[28:31], v[242:245], v[210:213], v[28:31]
	v_mfma_f32_16x16x32_bf16 v[20:23], v[234:237], v[218:221], v[20:23]
	v_mfma_f32_16x16x32_bf16 v[12:15], v[242:245], v[218:221], v[12:15]
	v_mfma_f32_16x16x32_bf16 v[4:7], v[234:237], v[226:229], v[4:7]
	v_mfma_f32_16x16x32_bf16 v[0:3], v[242:245], v[226:229], v[0:3]
	s_barrier
	s_add_i32 s78, 0, 0x18000
	ds_read_b128 v[120:123], v250
	ds_read_b128 v[124:127], v250 offset:1024
	ds_read_b128 v[132:135], v250 offset:2048
	ds_read_b128 v[136:139], v250 offset:3072
	s_add_u32 s34, s34, 0x200000
	s_addc_u32 s35, s35, 0
	s_mov_b32 m0, s54
	ds_read_b128 v[186:189], v185 offset:32768
	ds_read_b128 v[190:193], v185 offset:33792
	ds_read_b128 v[206:209], v185 offset:34816
	ds_read_b128 v[210:213], v185 offset:35840
	ds_read_b128 v[214:217], v185 offset:36864
	ds_read_b128 v[218:221], v185 offset:37888
	ds_read_b128 v[222:225], v185 offset:38912
	ds_read_b128 v[226:229], v185 offset:39936
	global_load_lds_dwordx4 v148, s[34:35]
	s_mov_b32 m0, s55
	s_nop 0
	global_load_lds_dwordx4 v146, s[34:35]
	s_waitcnt lgkmcnt(8)
	s_barrier
	s_waitcnt lgkmcnt(0)
	v_mfma_f32_16x16x32_bf16 v[140:143], v[120:123], v[186:189], v[140:143]
	v_mfma_f32_16x16x32_bf16 v[128:131], v[132:135], v[186:189], v[128:131]
	v_mfma_f32_16x16x32_bf16 v[112:115], v[120:123], v[206:209], v[112:115]
	v_mfma_f32_16x16x32_bf16 v[104:107], v[132:135], v[206:209], v[104:107]
	v_mfma_f32_16x16x32_bf16 v[96:99], v[120:123], v[214:217], v[96:99]
	v_mfma_f32_16x16x32_bf16 v[88:91], v[132:135], v[214:217], v[88:91]
	v_mfma_f32_16x16x32_bf16 v[80:83], v[120:123], v[222:225], v[80:83]
	v_mfma_f32_16x16x32_bf16 v[72:75], v[132:135], v[222:225], v[72:75]
	v_mfma_f32_16x16x32_bf16 v[140:143], v[124:127], v[190:193], v[140:143]
	v_mfma_f32_16x16x32_bf16 v[128:131], v[136:139], v[190:193], v[128:131]
	v_mfma_f32_16x16x32_bf16 v[112:115], v[124:127], v[210:213], v[112:115]
	v_mfma_f32_16x16x32_bf16 v[104:107], v[136:139], v[210:213], v[104:107]
	v_mfma_f32_16x16x32_bf16 v[96:99], v[124:127], v[218:221], v[96:99]
	v_mfma_f32_16x16x32_bf16 v[88:91], v[136:139], v[218:221], v[88:91]
	v_mfma_f32_16x16x32_bf16 v[80:83], v[124:127], v[226:229], v[80:83]
	v_mfma_f32_16x16x32_bf16 v[72:75], v[136:139], v[226:229], v[72:75]
	s_barrier
	s_add_i32 s34, 0, 0x1c000
	s_add_i32 s35, s78, s51
	s_add_u32 s100, s22, 0x80
	s_addc_u32 s101, s23, 0
	s_mov_b32 m0, s35
	ds_read_b128 v[230:233], v251
	ds_read_b128 v[234:237], v251 offset:1024
	ds_read_b128 v[238:241], v251 offset:2048
	ds_read_b128 v[242:245], v251 offset:3072
	global_load_lds_dwordx4 v152, s[100:101]
	s_add_i32 m0, s35, 0x2000
	s_nop 0
	global_load_lds_dwordx4 v144, s[100:101]
	s_barrier
	s_waitcnt lgkmcnt(0)
	v_mfma_f32_16x16x32_bf16 v[116:119], v[230:233], v[186:189], v[116:119]
	v_mfma_f32_16x16x32_bf16 v[108:111], v[238:241], v[186:189], v[108:111]
	v_mfma_f32_16x16x32_bf16 v[100:103], v[230:233], v[206:209], v[100:103]
	v_mfma_f32_16x16x32_bf16 v[92:95], v[238:241], v[206:209], v[92:95]
	v_mfma_f32_16x16x32_bf16 v[84:87], v[230:233], v[214:217], v[84:87]
	v_mfma_f32_16x16x32_bf16 v[76:79], v[238:241], v[214:217], v[76:79]
	v_mfma_f32_16x16x32_bf16 v[68:71], v[230:233], v[222:225], v[68:71]
	v_mfma_f32_16x16x32_bf16 v[64:67], v[238:241], v[222:225], v[64:67]
	v_mfma_f32_16x16x32_bf16 v[116:119], v[234:237], v[190:193], v[116:119]
	v_mfma_f32_16x16x32_bf16 v[108:111], v[242:245], v[190:193], v[108:111]
	v_mfma_f32_16x16x32_bf16 v[100:103], v[234:237], v[210:213], v[100:103]
	v_mfma_f32_16x16x32_bf16 v[92:95], v[242:245], v[210:213], v[92:95]
	v_mfma_f32_16x16x32_bf16 v[84:87], v[234:237], v[218:221], v[84:87]
	v_mfma_f32_16x16x32_bf16 v[76:79], v[242:245], v[218:221], v[76:79]
	v_mfma_f32_16x16x32_bf16 v[68:71], v[234:237], v[226:229], v[68:71]
	v_mfma_f32_16x16x32_bf16 v[64:67], v[242:245], v[226:229], v[64:67]
	s_barrier
	s_mov_b32 m0, s60
	ds_read_b128 v[186:189], v185 offset:49152
	ds_read_b128 v[190:193], v185 offset:50176
	ds_read_b128 v[206:209], v185 offset:51200
	ds_read_b128 v[210:213], v185 offset:52224
	ds_read_b128 v[214:217], v185 offset:53248
	ds_read_b128 v[218:221], v185 offset:54272
	ds_read_b128 v[222:225], v185 offset:55296
	ds_read_b128 v[226:229], v185 offset:56320
	global_load_lds_dwordx4 v148, s[98:99]
	s_mov_b32 m0, s61
	s_nop 0
	global_load_lds_dwordx4 v146, s[98:99]
	s_barrier
	s_waitcnt lgkmcnt(0)
	v_mfma_f32_16x16x32_bf16 v[60:63], v[120:123], v[186:189], v[60:63]
	v_mfma_f32_16x16x32_bf16 v[56:59], v[132:135], v[186:189], v[56:59]
	v_mfma_f32_16x16x32_bf16 v[48:51], v[120:123], v[206:209], v[48:51]
	v_mfma_f32_16x16x32_bf16 v[40:43], v[132:135], v[206:209], v[40:43]
	v_mfma_f32_16x16x32_bf16 v[32:35], v[120:123], v[214:217], v[32:35]
	v_mfma_f32_16x16x32_bf16 v[24:27], v[132:135], v[214:217], v[24:27]
	v_mfma_f32_16x16x32_bf16 v[16:19], v[120:123], v[222:225], v[16:19]
	v_mfma_f32_16x16x32_bf16 v[8:11], v[132:135], v[222:225], v[8:11]
	v_mfma_f32_16x16x32_bf16 v[60:63], v[124:127], v[190:193], v[60:63]
	v_mfma_f32_16x16x32_bf16 v[56:59], v[136:139], v[190:193], v[56:59]
	v_mfma_f32_16x16x32_bf16 v[48:51], v[124:127], v[210:213], v[48:51]
	v_mfma_f32_16x16x32_bf16 v[40:43], v[136:139], v[210:213], v[40:43]
	v_mfma_f32_16x16x32_bf16 v[32:35], v[124:127], v[218:221], v[32:35]
	v_mfma_f32_16x16x32_bf16 v[24:27], v[136:139], v[218:221], v[24:27]
	v_mfma_f32_16x16x32_bf16 v[16:19], v[124:127], v[226:229], v[16:19]
	v_mfma_f32_16x16x32_bf16 v[8:11], v[136:139], v[226:229], v[8:11]
	s_barrier
	s_add_u32 s22, s22, 0x200080
	s_addc_u32 s23, s23, 0
	s_add_i32 s34, s34, s51
	s_mov_b32 m0, s34
	s_nop 0
	global_load_lds_dwordx4 v152, s[22:23]
	s_add_i32 m0, s34, 0x2000
	s_nop 0
	global_load_lds_dwordx4 v144, s[22:23]
	s_add_i32 s69, s69, 2
	s_add_u32 s20, s20, 0x100
	s_addc_u32 s21, s21, 0
	s_add_u32 s63, s63, 0x100
	s_addc_u32 s68, s68, 0
	s_cmpk_gt_u32 s69, 0x7d
	s_waitcnt vmcnt(6)
	s_barrier
	v_mfma_f32_16x16x32_bf16 v[52:55], v[230:233], v[186:189], v[52:55]
	v_mfma_f32_16x16x32_bf16 v[44:47], v[238:241], v[186:189], v[44:47]
	v_mfma_f32_16x16x32_bf16 v[36:39], v[230:233], v[206:209], v[36:39]
	v_mfma_f32_16x16x32_bf16 v[28:31], v[238:241], v[206:209], v[28:31]
	v_mfma_f32_16x16x32_bf16 v[20:23], v[230:233], v[214:217], v[20:23]
	v_mfma_f32_16x16x32_bf16 v[12:15], v[238:241], v[214:217], v[12:15]
	v_mfma_f32_16x16x32_bf16 v[4:7], v[230:233], v[222:225], v[4:7]
	v_mfma_f32_16x16x32_bf16 v[0:3], v[238:241], v[222:225], v[0:3]
	v_mfma_f32_16x16x32_bf16 v[52:55], v[234:237], v[190:193], v[52:55]
	v_mfma_f32_16x16x32_bf16 v[44:47], v[242:245], v[190:193], v[44:47]
	v_mfma_f32_16x16x32_bf16 v[36:39], v[234:237], v[210:213], v[36:39]
	v_mfma_f32_16x16x32_bf16 v[28:31], v[242:245], v[210:213], v[28:31]
	v_mfma_f32_16x16x32_bf16 v[20:23], v[234:237], v[218:221], v[20:23]
	v_mfma_f32_16x16x32_bf16 v[12:15], v[242:245], v[218:221], v[12:15]
	v_mfma_f32_16x16x32_bf16 v[4:7], v[234:237], v[226:229], v[4:7]
	v_mfma_f32_16x16x32_bf16 v[0:3], v[242:245], v[226:229], v[0:3]
	s_barrier
	s_cbranch_scc0 .LBB0_836
	v_readlane_b32 s98, v246, 0
	v_readlane_b32 s99, v246, 1
	s_cmp_eq_u32 s99, 0
	s_cbranch_scc1 .Lm2_epi
	s_and_b32 s100, s2, 0x7f
	s_lshl_b32 s100, s100, 18
	s_add_u32 s100, s100, 0x29800000
	s_add_u32 s100, s46, s100
	s_addc_u32 s101, s47, 0
	v_lshlrev_b32_e32 v186, 4, v182
	s_cmp_eq_u32 s99, 1
	s_cbranch_scc1 .Lm2_put_partial
	s_and_b32 s6, s2, 0x7f
	s_lshl_b32 s6, s6, 6
	s_add_u32 s6, s6, 0x2970a000
	s_add_u32 s6, s46, s6
	s_addc_u32 s7, s47, 0
	v_mov_b32_e32 v187, 0
	s_mov_b32 s99, 0
